# speedup vs baseline: 1.1111x; 1.0022x over previous
; __device__ __forceinline__ float bf2f(unsigned h) { return __uint_as_float(h << 16); }
; template <bool FINAL>
; __device__ void phase_lru(const Params& p, int l, unsigned char* smem) {
;     ...
;     if (it + step < NIT) load_x(it + step, x0, x1, x2);
;     {
;       const int ch = nb * 64 + e_;
;       const float cw0 = p.conv_w[(l * 4 + 0) * 512 + ch], cw1 = p.conv_w[(l * 4 + 1) * 512 + ch],
;                   cw2 = p.conv_w[(l * 4 + 2) * 512 + ch], cw3 = p.conv_w[(l * 4 + 3) * 512 + ch];
;       const float cb = p.conv_b[l * 512 + ch];
;       float xv[19];
; #pragma unroll
;       for (int k = 0; k < 19; ++k) xv[k] = bf2f(xs[(qd * 16 + k) * 64 + e_]);
; #pragma unroll
;       for (int tt = 0; tt < 16; ++tt) {
;         const int t = qd * 16 + tt;
;         const float u = cb + xv[tt] * cw0 + xv[tt + 1] * cw1 + xv[tt + 2] * cw2 + xv[tt + 3] * cw3;
;         u32[t * 64 + e_] = u;
;         ub[t * 72 + e_] = (u16)f2bf(u);
;       }
;     }
.LBB0_209:
	v_or_b32_e32 v26, s40, v38
	v_or_b32_e32 v20, s20, v26
	v_readlane_b32 s4, v250, 37
	v_ashrrev_i32_e32 v21, 31, v20
	v_readlane_b32 s6, v250, 39
	v_readlane_b32 s7, v250, 40
	v_readlane_b32 s8, v250, 41
	v_readlane_b32 s9, v250, 42
	v_lshl_add_u64 v[22:23], v[20:21], 2, s[6:7]
	v_add_co_u32_e32 v24, vcc, 0x1000, v22
	global_load_dword v21, v[22:23], off
	global_load_dword v20, v[22:23], off offset:2048
	v_addc_co_u32_e32 v25, vcc, 0, v23, vcc
	global_load_dword v23, v[24:25], off
	global_load_dword v22, v[24:25], off offset:2048
	v_or_b32_e32 v24, s21, v26
	v_ashrrev_i32_e32 v25, 31, v24
	v_lshl_add_u64 v[24:25], v[24:25], 2, s[8:9]
	global_load_dword v24, v[24:25], off
	ds_read_u16 v25, v158
	ds_read_u16 v26, v158 offset:128
	ds_read_u16 v27, v158 offset:256
	ds_read_u16 v28, v158 offset:384
	ds_read_u16 v29, v158 offset:512
	s_waitcnt lgkmcnt(4)
	v_lshlrev_b32_e32 v25, 16, v25
	s_waitcnt lgkmcnt(3)
	v_lshlrev_b32_e32 v26, 16, v26
	s_waitcnt lgkmcnt(2)
	v_lshlrev_b32_e32 v27, 16, v27
	s_waitcnt lgkmcnt(1)
	v_lshlrev_b32_e32 v28, 16, v28
	v_add_u32_e32 v69, v96, v102
	ds_read_u16 v30, v158 offset:640
	ds_read_u16 v31, v158 offset:768
	ds_read_u16 v32, v158 offset:896
	ds_read_u16 v33, v158 offset:1024
	ds_read_u16 v34, v158 offset:1152
	ds_read_u16 v35, v158 offset:1280
	ds_read_u16 v61, v158 offset:1408
	ds_read_u16 v62, v158 offset:1536
	ds_read_u16 v63, v158 offset:1664
	ds_read_u16 v64, v158 offset:1792
	ds_read_u16 v65, v158 offset:1920
	ds_read_u16 v66, v158 offset:2048
	ds_read_u16 v67, v158 offset:2176
	ds_read_u16 v68, v158 offset:2304
	s_waitcnt lgkmcnt(14)
	v_lshlrev_b32_e32 v29, 16, v29
	s_waitcnt lgkmcnt(13)
	v_lshlrev_b32_e32 v30, 16, v30
	s_waitcnt lgkmcnt(12)
	v_lshlrev_b32_e32 v31, 16, v31
	s_waitcnt lgkmcnt(11)
	v_lshlrev_b32_e32 v32, 16, v32
	s_waitcnt lgkmcnt(10)
	v_lshlrev_b32_e32 v33, 16, v33
	s_waitcnt lgkmcnt(9)
	v_lshlrev_b32_e32 v34, 16, v34
	s_waitcnt lgkmcnt(8)
	v_lshlrev_b32_e32 v35, 16, v35
	s_waitcnt lgkmcnt(7)
	v_lshlrev_b32_e32 v61, 16, v61
	s_waitcnt lgkmcnt(6)
	v_lshlrev_b32_e32 v62, 16, v62
	s_waitcnt lgkmcnt(5)
	v_lshlrev_b32_e32 v63, 16, v63
	s_waitcnt lgkmcnt(4)
	v_lshlrev_b32_e32 v64, 16, v64
	s_waitcnt lgkmcnt(3)
	v_lshlrev_b32_e32 v65, 16, v65
	s_waitcnt lgkmcnt(2)
	v_lshlrev_b32_e32 v66, 16, v66
	s_waitcnt lgkmcnt(1)
	v_lshlrev_b32_e32 v67, 16, v67
	s_waitcnt lgkmcnt(0)
	v_lshlrev_b32_e32 v68, 16, v68
	v_readlane_b32 s5, v250, 38
	s_mov_b64 s[4:5], 0x10000
	s_mov_b32 s6, 0xbe800000
	s_mov_b64 s[8:9], 0x10800
	s_ashr_i32 s93, s92, 31
	v_readlane_b32 s10, v250, 43
	v_readlane_b32 s11, v250, 44
	v_readlane_b32 s12, v250, 45
	v_readlane_b32 s13, v250, 46
	v_readlane_b32 s14, v250, 47
	v_readlane_b32 s15, v250, 48
	v_readlane_b32 s16, v250, 49
	v_readlane_b32 s17, v250, 50
	v_readlane_b32 s18, v250, 51
	v_readlane_b32 s19, v250, 52
	s_waitcnt vmcnt(0)
	v_fma_f32 v25, v21, v25, v24
	v_fmac_f32_e32 v25, v20, v26
	v_fmac_f32_e32 v25, v23, v27
	v_fmac_f32_e32 v25, v22, v28
	ds_write_b32 v69, v25 offset:8704
	v_cvt_pk_bf16_f32 v25, v25, s0
	ds_write_b16 v159, v25 offset:25088
	v_fma_f32 v25, v21, v26, v24
	v_fmac_f32_e32 v25, v20, v27
	v_fmac_f32_e32 v25, v23, v28
	v_fmac_f32_e32 v25, v22, v29
	v_add_u32_e32 v26, v96, v103
	ds_write_b32 v26, v25 offset:8704
	v_cvt_pk_bf16_f32 v25, v25, s0
	ds_write_b16 v160, v25 offset:25088
	v_fma_f32 v25, v21, v27, v24
	v_fmac_f32_e32 v25, v20, v28
	v_fmac_f32_e32 v25, v23, v29
	v_fmac_f32_e32 v25, v22, v30
	v_add_u32_e32 v26, v96, v104
	ds_write_b32 v26, v25 offset:8704
	v_cvt_pk_bf16_f32 v25, v25, s0
	ds_write_b16 v160, v25 offset:25232
	v_fma_f32 v25, v21, v28, v24
	v_fmac_f32_e32 v25, v20, v29
	v_fmac_f32_e32 v25, v23, v30
	v_fmac_f32_e32 v25, v22, v31
	v_add_u32_e32 v26, v96, v105
	ds_write_b32 v26, v25 offset:8704
	v_cvt_pk_bf16_f32 v25, v25, s0
	ds_write_b16 v160, v25 offset:25376
	v_fma_f32 v25, v21, v29, v24
	v_fmac_f32_e32 v25, v20, v30
	v_fmac_f32_e32 v25, v23, v31
	v_fmac_f32_e32 v25, v22, v32
	v_add_u32_e32 v26, v96, v106
	ds_write_b32 v26, v25 offset:8704
	v_cvt_pk_bf16_f32 v25, v25, s0
	ds_write_b16 v160, v25 offset:25520
	v_fma_f32 v25, v21, v30, v24
	v_fmac_f32_e32 v25, v20, v31
	v_fmac_f32_e32 v25, v23, v32
	v_fmac_f32_e32 v25, v22, v33
	v_add_u32_e32 v26, v96, v107
	ds_write_b32 v26, v25 offset:8704
	v_cvt_pk_bf16_f32 v25, v25, s0
	ds_write_b16 v160, v25 offset:25664
	v_fma_f32 v25, v21, v31, v24
	v_fmac_f32_e32 v25, v20, v32
	v_fmac_f32_e32 v25, v23, v33
	v_fmac_f32_e32 v25, v22, v34
	v_add_u32_e32 v26, v96, v108
	ds_write_b32 v26, v25 offset:8704
	v_cvt_pk_bf16_f32 v25, v25, s0
	ds_write_b16 v160, v25 offset:25808
	v_fma_f32 v25, v21, v32, v24
	v_fmac_f32_e32 v25, v20, v33
	v_fmac_f32_e32 v25, v23, v34
	v_fmac_f32_e32 v25, v22, v35
	v_add_u32_e32 v26, v96, v109
	ds_write_b32 v26, v25 offset:8704
	v_cvt_pk_bf16_f32 v25, v25, s0
	ds_write_b16 v160, v25 offset:25952
	v_fma_f32 v25, v21, v33, v24
	v_fmac_f32_e32 v25, v20, v34
	v_fmac_f32_e32 v25, v23, v35
	v_fmac_f32_e32 v25, v22, v61
	v_add_u32_e32 v26, v96, v110
	ds_write_b32 v26, v25 offset:8704
	v_cvt_pk_bf16_f32 v25, v25, s0
	ds_write_b16 v160, v25 offset:26096
	v_fma_f32 v25, v21, v34, v24
	v_fmac_f32_e32 v25, v20, v35
	v_fmac_f32_e32 v25, v23, v61
	v_fmac_f32_e32 v25, v22, v62
	v_add_u32_e32 v26, v96, v111
	ds_write_b32 v26, v25 offset:8704
	v_cvt_pk_bf16_f32 v25, v25, s0
	ds_write_b16 v160, v25 offset:26240
	v_fma_f32 v25, v21, v35, v24
	v_fmac_f32_e32 v25, v20, v61
	v_fmac_f32_e32 v25, v23, v62
	v_fmac_f32_e32 v25, v22, v63
	v_add_u32_e32 v26, v96, v112
	ds_write_b32 v26, v25 offset:8704
	v_cvt_pk_bf16_f32 v25, v25, s0
	ds_write_b16 v160, v25 offset:26384
	v_fma_f32 v25, v21, v61, v24
; __device__ __forceinline__ float sigmoidf_(float x) { return __builtin_amdgcn_rcpf(1.0f + __expf(-x)); }
; template <bool FINAL>
; __device__ void phase_lru(const Params& p, int l, unsigned char* smem) {
;     ...
;       for (int tt = 0; tt < 16; ++tt) {
;         const int t = qd * 16 + tt;
;         const float u = cb + xv[tt] * cw0 + xv[tt + 1] * cw1 + xv[tt + 2] * cw2 + xv[tt + 3] * cw3;
;         u32[t * 64 + e_] = u;
;         ub[t * 72 + e_] = (u16)f2bf(u);
;       }
;     }
;     __syncthreads();
;     if (FINAL) {
;       *(uint4*)(xs + (tid >> 3) * 64 + (tid & 7) * 8) = gz0;
;       *(uint4*)(xs + ((tid >> 3) + 32) * 64 + (tid & 7) * 8) = gz1;
;     }
;     ...
;           const int e0 = et * 16 + 4 * g, ch0 = nb * 64 + e0;
;           const float4 ba4 = *(const float4*)(p.ba + (l * 2 + d) * 512 + ch0);
;           const float4 bx4 = *(const float4*)(p.bx + (l * 2 + d) * 512 + ch0);
;           const float4 sp4 = *(const float4*)(p.SP8 + (l * 2 + d) * 512 + ch0);
;           const float4 uu = *(const float4*)(u32 + t * 64 + e0);
;           const float* bap = (const float*)&ba4; const float* bxp = (const float*)&bx4;
;           const float* spp = (const float*)&sp4; const float* uup = (const float*)&uu;
;           f32x4 av, bv;
; #pragma unroll
;           for (int j = 0; j < 4; ++j) {
;             float r = sigmoidf_(ar[j] + bap[j]);
;             float ig = sigmoidf_(ai[j] + bxp[j]);
;             float la = spp[j] * r;
;             float av_ = __expf(la);
;             float t2 = 2.0f * la;
;             float ser = -t2 * (1.f + t2 * 0.5f * (1.f + t2 * (1.f / 3.f) * (1.f + t2 * 0.25f * (1.f + t2 * 0.2f))));
;             float om = (t2 > -0.25f) ? ser : (1.0f - av_ * av_);
;             av[j] = av_;
;             bv[j] = __builtin_amdgcn_sqrtf(om) * ig * uup[j];
;           }
;           *(f32x4*)(sa + t * 64 + e0) = av;
;           *(f32x4*)(sb + t * 64 + e0) = bv;
;         }
	v_fmac_f32_e32 v25, v20, v62
	v_fmac_f32_e32 v25, v23, v63
	v_fmac_f32_e32 v25, v22, v64
	v_add_u32_e32 v26, v96, v113
	ds_write_b32 v26, v25 offset:8704
	v_cvt_pk_bf16_f32 v25, v25, s0
	ds_write_b16 v160, v25 offset:26528
	v_fma_f32 v25, v21, v62, v24
	v_fmac_f32_e32 v25, v20, v63
	v_fmac_f32_e32 v25, v23, v64
	v_fmac_f32_e32 v25, v22, v65
	v_add_u32_e32 v26, v96, v114
	ds_write_b32 v26, v25 offset:8704
	v_cvt_pk_bf16_f32 v25, v25, s0
	ds_write_b16 v160, v25 offset:26672
	v_fma_f32 v25, v21, v63, v24
	v_fmac_f32_e32 v25, v20, v64
	v_fmac_f32_e32 v25, v23, v65
	v_fmac_f32_e32 v25, v22, v66
	v_add_u32_e32 v26, v96, v115
	ds_write_b32 v26, v25 offset:8704
	v_cvt_pk_bf16_f32 v25, v25, s0
	ds_write_b16 v160, v25 offset:26816
	v_fma_f32 v25, v21, v64, v24
	v_fmac_f32_e32 v24, v21, v65
	v_fmac_f32_e32 v24, v20, v66
	v_fmac_f32_e32 v24, v23, v67
	v_fmac_f32_e32 v25, v20, v65
	v_fmac_f32_e32 v24, v22, v68
	v_add_u32_e32 v20, v96, v117
	ds_write_b32 v20, v24 offset:8704
	v_cvt_pk_bf16_f32 v20, v24, s0
	v_fmac_f32_e32 v25, v23, v66
	ds_write_b16 v160, v20 offset:27104
	v_or_b32_e32 v20, s40, v39
	v_fmac_f32_e32 v25, v22, v67
	v_add_u32_e32 v26, v96, v116
	v_lshlrev_b32_e32 v144, 7, v20
	ds_write_b32 v26, v25 offset:8704
	v_cvt_pk_bf16_f32 v25, v25, s0
	v_lshl_add_u64 v[20:21], s[42:43], 0, v[144:145]
	v_lshlrev_b32_e32 v62, 1, v50
	v_mov_b32_e32 v63, v145
	ds_write_b16 v160, v25 offset:26960
	s_waitcnt lgkmcnt(0)
	s_barrier
	ds_write_b128 v41, v[12:15]
	ds_write_b128 v41, v[16:19] offset:4096
	s_mov_b32 s5, 0x3e4ccccd
	global_load_dwordx4 v[196:199], v231, s[58:59]
	global_load_dwordx4 v[200:203], v231, s[60:61]
	global_load_dwordx4 v[32:35], v231, s[62:63]
	ds_read_b128 v[12:15], v229 offset:25088
	ds_read_b128 v[16:19], v229 offset:25152
	ds_read_b128 v[28:31], v230 offset:8704
	s_waitcnt lgkmcnt(1)
	v_mfma_f32_16x16x32_bf16 v[20:23], v[180:183], v[12:15], 0
	v_mfma_f32_16x16x32_bf16 v[24:27], v[188:191], v[12:15], 0
	v_mfma_f32_16x16x32_bf16 v[20:23], v[184:187], v[16:19], v[20:23]
	v_mfma_f32_16x16x32_bf16 v[24:27], v[192:195], v[16:19], v[24:27]
	s_waitcnt vmcnt(0)
	v_mul_f32_e32 v196, 0xbfb8aa3b, v196
	v_mul_f32_e32 v197, 0xbfb8aa3b, v197
	v_mul_f32_e32 v198, 0xbfb8aa3b, v198
	v_mul_f32_e32 v199, 0xbfb8aa3b, v199
	v_mul_f32_e32 v200, 0xbfb8aa3b, v200
	v_mul_f32_e32 v201, 0xbfb8aa3b, v201
	v_mul_f32_e32 v202, 0xbfb8aa3b, v202
	v_mul_f32_e32 v203, 0xbfb8aa3b, v203
	v_add_f32_e32 v170, v32, v32
	v_add_f32_e32 v171, v33, v33
	v_add_f32_e32 v172, v34, v34
	v_add_f32_e32 v173, v35, v35
	v_mul_f32_e32 v174, 0x3fb8aa3b, v32
	v_mul_f32_e32 v175, 0x3fb8aa3b, v33
	v_mul_f32_e32 v176, 0x3fb8aa3b, v34
	v_mul_f32_e32 v177, 0x3fb8aa3b, v35
	s_nop 7
	s_nop 3
	s_waitcnt lgkmcnt(0)
	v_fmamk_f32 v20, v20, 0xbfb8aa3b, v196
	v_fmamk_f32 v21, v21, 0xbfb8aa3b, v197
	v_fmamk_f32 v24, v24, 0xbfb8aa3b, v200
	v_fmamk_f32 v25, v25, 0xbfb8aa3b, v201
	v_exp_f32_e32 v20, v20
	v_exp_f32_e32 v21, v21
	v_exp_f32_e32 v24, v24
	v_exp_f32_e32 v25, v25
	v_add_f32_e32 v20, 1.0, v20
	v_add_f32_e32 v21, 1.0, v21
	v_add_f32_e32 v24, 1.0, v24
	v_add_f32_e32 v25, 1.0, v25
	v_rcp_f32_e32 v20, v20
	v_rcp_f32_e32 v21, v21
	v_rcp_f32_e32 v24, v24
	v_rcp_f32_e32 v25, v25
	v_pk_mul_f32 v[14:15], v[20:21], v[170:171]
	v_pk_mul_f32 v[12:13], v[20:21], v[174:175]
	s_nop 0
	v_exp_f32_e32 v20, v12
	v_exp_f32_e32 v21, v13
	v_fmaak_f32 v16, v14, v205, 0x3d2aaaab
	v_fmaak_f32 v19, v15, v205, 0x3d2aaaab
	v_fmaak_f32 v16, v16, v14, 0x3e2aaaab
	v_fmaak_f32 v19, v19, v15, 0x3e2aaaab
	v_fma_f32 v16, v16, v14, 0.5
	v_fma_f32 v19, v19, v15, 0.5
	v_fma_f32 v16, v16, v14, 1.0
	v_fma_f32 v19, v19, v15, 1.0
	v_mul_f32_e64 v17, v16, -v14
	v_mul_f32_e64 v12, v19, -v15
	v_fma_f32 v16, -v20, v20, 1.0
	v_cmp_lt_f32_e32 vcc, s6, v14
	v_fma_f32 v13, -v21, v21, 1.0
	s_nop 0
	v_cndmask_b32_e32 v16, v16, v17, vcc
	v_cmp_lt_f32_e32 vcc, s6, v15
	v_sqrt_f32_e32 v16, v16
	s_nop 1
	v_cndmask_b32_e32 v17, v13, v12, vcc
	v_sqrt_f32_e32 v17, v17
	s_nop 0
	v_pk_mul_f32 v[24:25], v[24:25], v[16:17]
	s_nop 0
	v_pk_mul_f32 v[24:25], v[28:29], v[24:25]
	v_fmamk_f32 v22, v22, 0xbfb8aa3b, v198
	v_fmamk_f32 v23, v23, 0xbfb8aa3b, v199
	v_fmamk_f32 v26, v26, 0xbfb8aa3b, v202
	v_fmamk_f32 v27, v27, 0xbfb8aa3b, v203
	v_exp_f32_e32 v22, v22
	v_exp_f32_e32 v23, v23
	v_exp_f32_e32 v26, v26
	v_exp_f32_e32 v27, v27
	v_add_f32_e32 v22, 1.0, v22
	v_add_f32_e32 v23, 1.0, v23
	v_add_f32_e32 v26, 1.0, v26
	v_add_f32_e32 v27, 1.0, v27
	v_rcp_f32_e32 v22, v22
	v_rcp_f32_e32 v23, v23
	v_rcp_f32_e32 v26, v26
	v_rcp_f32_e32 v27, v27
	v_pk_mul_f32 v[14:15], v[22:23], v[172:173]
	v_pk_mul_f32 v[12:13], v[22:23], v[176:177]
	s_nop 0
	v_exp_f32_e32 v22, v12
	v_exp_f32_e32 v23, v13
	v_fmaak_f32 v16, v14, v205, 0x3d2aaaab
	v_fmaak_f32 v19, v15, v205, 0x3d2aaaab
	v_fmaak_f32 v16, v16, v14, 0x3e2aaaab
	v_fmaak_f32 v19, v19, v15, 0x3e2aaaab
	v_fma_f32 v16, v16, v14, 0.5
	v_fma_f32 v19, v19, v15, 0.5
	v_fma_f32 v16, v16, v14, 1.0
	v_fma_f32 v19, v19, v15, 1.0
	v_mul_f32_e64 v17, v16, -v14
	v_mul_f32_e64 v12, v19, -v15
	v_fma_f32 v16, -v22, v22, 1.0
	v_cmp_lt_f32_e32 vcc, s6, v14
	v_fma_f32 v13, -v23, v23, 1.0
	s_nop 0
	v_cndmask_b32_e32 v16, v16, v17, vcc
	v_cmp_lt_f32_e32 vcc, s6, v15
	v_sqrt_f32_e32 v16, v16
	s_nop 1
	v_cndmask_b32_e32 v17, v13, v12, vcc
	v_sqrt_f32_e32 v17, v17
	s_nop 0
	v_pk_mul_f32 v[26:27], v[26:27], v[16:17]
	s_nop 0
	v_pk_mul_f32 v[26:27], v[30:31], v[26:27]
	ds_write_b128 v204, v[20:23] offset:34304
	ds_write_b128 v204, v[24:27] offset:50688
	ds_read_b128 v[12:15], v229 offset:27392
	ds_read_b128 v[16:19], v229 offset:27456
	ds_read_b128 v[28:31], v230 offset:12800
	s_waitcnt lgkmcnt(1)
; __device__ __forceinline__ float sigmoidf_(float x) { return __builtin_amdgcn_rcpf(1.0f + __expf(-x)); }
; template <bool FINAL>
; __device__ void phase_lru(const Params& p, int l, unsigned char* smem) {
;     ...
;           const int e0 = et * 16 + 4 * g, ch0 = nb * 64 + e0;
;           const float4 ba4 = *(const float4*)(p.ba + (l * 2 + d) * 512 + ch0);
;           const float4 bx4 = *(const float4*)(p.bx + (l * 2 + d) * 512 + ch0);
;           const float4 sp4 = *(const float4*)(p.SP8 + (l * 2 + d) * 512 + ch0);
;           const float4 uu = *(const float4*)(u32 + t * 64 + e0);
;           const float* bap = (const float*)&ba4; const float* bxp = (const float*)&bx4;
;           const float* spp = (const float*)&sp4; const float* uup = (const float*)&uu;
;           f32x4 av, bv;
; #pragma unroll
;           for (int j = 0; j < 4; ++j) {
;             float r = sigmoidf_(ar[j] + bap[j]);
;             float ig = sigmoidf_(ai[j] + bxp[j]);
;             float la = spp[j] * r;
;             float av_ = __expf(la);
;             float t2 = 2.0f * la;
;             float ser = -t2 * (1.f + t2 * 0.5f * (1.f + t2 * (1.f / 3.f) * (1.f + t2 * 0.25f * (1.f + t2 * 0.2f))));
;             float om = (t2 > -0.25f) ? ser : (1.0f - av_ * av_);
;             av[j] = av_;
;             bv[j] = __builtin_amdgcn_sqrtf(om) * ig * uup[j];
;           }
;           *(f32x4*)(sa + t * 64 + e0) = av;
;           *(f32x4*)(sb + t * 64 + e0) = bv;
;         }
	v_mfma_f32_16x16x32_bf16 v[20:23], v[180:183], v[12:15], 0
	v_mfma_f32_16x16x32_bf16 v[24:27], v[188:191], v[12:15], 0
	v_mfma_f32_16x16x32_bf16 v[20:23], v[184:187], v[16:19], v[20:23]
	v_mfma_f32_16x16x32_bf16 v[24:27], v[192:195], v[16:19], v[24:27]
	s_nop 7
	s_nop 3
	s_waitcnt lgkmcnt(0)
	v_fmamk_f32 v20, v20, 0xbfb8aa3b, v196
	v_fmamk_f32 v21, v21, 0xbfb8aa3b, v197
	v_fmamk_f32 v24, v24, 0xbfb8aa3b, v200
	v_fmamk_f32 v25, v25, 0xbfb8aa3b, v201
	v_exp_f32_e32 v20, v20
	v_exp_f32_e32 v21, v21
	v_exp_f32_e32 v24, v24
	v_exp_f32_e32 v25, v25
	v_add_f32_e32 v20, 1.0, v20
	v_add_f32_e32 v21, 1.0, v21
	v_add_f32_e32 v24, 1.0, v24
	v_add_f32_e32 v25, 1.0, v25
	v_rcp_f32_e32 v20, v20
	v_rcp_f32_e32 v21, v21
	v_rcp_f32_e32 v24, v24
	v_rcp_f32_e32 v25, v25
	v_pk_mul_f32 v[14:15], v[20:21], v[170:171]
	v_pk_mul_f32 v[12:13], v[20:21], v[174:175]
	s_nop 0
	v_exp_f32_e32 v20, v12
	v_exp_f32_e32 v21, v13
	v_fmaak_f32 v16, v14, v205, 0x3d2aaaab
	v_fmaak_f32 v19, v15, v205, 0x3d2aaaab
	v_fmaak_f32 v16, v16, v14, 0x3e2aaaab
	v_fmaak_f32 v19, v19, v15, 0x3e2aaaab
	v_fma_f32 v16, v16, v14, 0.5
	v_fma_f32 v19, v19, v15, 0.5
	v_fma_f32 v16, v16, v14, 1.0
	v_fma_f32 v19, v19, v15, 1.0
	v_mul_f32_e64 v17, v16, -v14
	v_mul_f32_e64 v12, v19, -v15
	v_fma_f32 v16, -v20, v20, 1.0
	v_cmp_lt_f32_e32 vcc, s6, v14
	v_fma_f32 v13, -v21, v21, 1.0
	s_nop 0
	v_cndmask_b32_e32 v16, v16, v17, vcc
	v_cmp_lt_f32_e32 vcc, s6, v15
	v_sqrt_f32_e32 v16, v16
	s_nop 1
	v_cndmask_b32_e32 v17, v13, v12, vcc
	v_sqrt_f32_e32 v17, v17
	s_nop 0
	v_pk_mul_f32 v[24:25], v[24:25], v[16:17]
	s_nop 0
	v_pk_mul_f32 v[24:25], v[28:29], v[24:25]
	v_fmamk_f32 v22, v22, 0xbfb8aa3b, v198
	v_fmamk_f32 v23, v23, 0xbfb8aa3b, v199
	v_fmamk_f32 v26, v26, 0xbfb8aa3b, v202
	v_fmamk_f32 v27, v27, 0xbfb8aa3b, v203
	v_exp_f32_e32 v22, v22
	v_exp_f32_e32 v23, v23
	v_exp_f32_e32 v26, v26
	v_exp_f32_e32 v27, v27
	v_add_f32_e32 v22, 1.0, v22
	v_add_f32_e32 v23, 1.0, v23
	v_add_f32_e32 v26, 1.0, v26
	v_add_f32_e32 v27, 1.0, v27
	v_rcp_f32_e32 v22, v22
	v_rcp_f32_e32 v23, v23
	v_rcp_f32_e32 v26, v26
	v_rcp_f32_e32 v27, v27
	v_pk_mul_f32 v[14:15], v[22:23], v[172:173]
	v_pk_mul_f32 v[12:13], v[22:23], v[176:177]
	s_nop 0
	v_exp_f32_e32 v22, v12
	v_exp_f32_e32 v23, v13
	v_fmaak_f32 v16, v14, v205, 0x3d2aaaab
	v_fmaak_f32 v19, v15, v205, 0x3d2aaaab
	v_fmaak_f32 v16, v16, v14, 0x3e2aaaab
	v_fmaak_f32 v19, v19, v15, 0x3e2aaaab
	v_fma_f32 v16, v16, v14, 0.5
	v_fma_f32 v19, v19, v15, 0.5
	v_fma_f32 v16, v16, v14, 1.0
	v_fma_f32 v19, v19, v15, 1.0
	v_mul_f32_e64 v17, v16, -v14
	v_mul_f32_e64 v12, v19, -v15
	v_fma_f32 v16, -v22, v22, 1.0
	v_cmp_lt_f32_e32 vcc, s6, v14
	v_fma_f32 v13, -v23, v23, 1.0
	s_nop 0
	v_cndmask_b32_e32 v16, v16, v17, vcc
	v_cmp_lt_f32_e32 vcc, s6, v15
	v_sqrt_f32_e32 v16, v16
	s_nop 1
	v_cndmask_b32_e32 v17, v13, v12, vcc
	v_sqrt_f32_e32 v17, v17
	s_nop 0
	v_pk_mul_f32 v[26:27], v[26:27], v[16:17]
	s_nop 0
	v_pk_mul_f32 v[26:27], v[30:31], v[26:27]
	ds_write_b128 v204, v[20:23] offset:38400
	ds_write_b128 v204, v[24:27] offset:54784
	ds_read_b128 v[12:15], v229 offset:29696
	ds_read_b128 v[16:19], v229 offset:29760
	ds_read_b128 v[28:31], v230 offset:16896
	s_waitcnt lgkmcnt(1)
	v_mfma_f32_16x16x32_bf16 v[20:23], v[180:183], v[12:15], 0
	v_mfma_f32_16x16x32_bf16 v[24:27], v[188:191], v[12:15], 0
	v_mfma_f32_16x16x32_bf16 v[20:23], v[184:187], v[16:19], v[20:23]
	v_mfma_f32_16x16x32_bf16 v[24:27], v[192:195], v[16:19], v[24:27]
	s_nop 7
	s_nop 3
	s_waitcnt lgkmcnt(0)
	v_fmamk_f32 v20, v20, 0xbfb8aa3b, v196
	v_fmamk_f32 v21, v21, 0xbfb8aa3b, v197
	v_fmamk_f32 v24, v24, 0xbfb8aa3b, v200
	v_fmamk_f32 v25, v25, 0xbfb8aa3b, v201
	v_exp_f32_e32 v20, v20
	v_exp_f32_e32 v21, v21
	v_exp_f32_e32 v24, v24
	v_exp_f32_e32 v25, v25
	v_add_f32_e32 v20, 1.0, v20
	v_add_f32_e32 v21, 1.0, v21
	v_add_f32_e32 v24, 1.0, v24
	v_add_f32_e32 v25, 1.0, v25
	v_rcp_f32_e32 v20, v20
	v_rcp_f32_e32 v21, v21
	v_rcp_f32_e32 v24, v24
	v_rcp_f32_e32 v25, v25
	v_pk_mul_f32 v[14:15], v[20:21], v[170:171]
	v_pk_mul_f32 v[12:13], v[20:21], v[174:175]
	s_nop 0
	v_exp_f32_e32 v20, v12
	v_exp_f32_e32 v21, v13
	v_fmaak_f32 v16, v14, v205, 0x3d2aaaab
	v_fmaak_f32 v19, v15, v205, 0x3d2aaaab
	v_fmaak_f32 v16, v16, v14, 0x3e2aaaab
	v_fmaak_f32 v19, v19, v15, 0x3e2aaaab
	v_fma_f32 v16, v16, v14, 0.5
	v_fma_f32 v19, v19, v15, 0.5
	v_fma_f32 v16, v16, v14, 1.0
	v_fma_f32 v19, v19, v15, 1.0
	v_mul_f32_e64 v17, v16, -v14
	v_mul_f32_e64 v12, v19, -v15
	v_fma_f32 v16, -v20, v20, 1.0
	v_cmp_lt_f32_e32 vcc, s6, v14
	v_fma_f32 v13, -v21, v21, 1.0
	s_nop 0
	v_cndmask_b32_e32 v16, v16, v17, vcc
	v_cmp_lt_f32_e32 vcc, s6, v15
	v_sqrt_f32_e32 v16, v16
	s_nop 1
	v_cndmask_b32_e32 v17, v13, v12, vcc
	v_sqrt_f32_e32 v17, v17
	s_nop 0
	v_pk_mul_f32 v[24:25], v[24:25], v[16:17]
	s_nop 0
	v_pk_mul_f32 v[24:25], v[28:29], v[24:25]
	v_fmamk_f32 v22, v22, 0xbfb8aa3b, v198
	v_fmamk_f32 v23, v23, 0xbfb8aa3b, v199
	v_fmamk_f32 v26, v26, 0xbfb8aa3b, v202
	v_fmamk_f32 v27, v27, 0xbfb8aa3b, v203
	v_exp_f32_e32 v22, v22
	v_exp_f32_e32 v23, v23
	v_exp_f32_e32 v26, v26
	v_exp_f32_e32 v27, v27
	v_add_f32_e32 v22, 1.0, v22
	v_add_f32_e32 v23, 1.0, v23
	v_add_f32_e32 v26, 1.0, v26
	v_add_f32_e32 v27, 1.0, v27
	v_rcp_f32_e32 v22, v22
	v_rcp_f32_e32 v23, v23
	v_rcp_f32_e32 v26, v26
	v_rcp_f32_e32 v27, v27
	v_pk_mul_f32 v[14:15], v[22:23], v[172:173]
	v_pk_mul_f32 v[12:13], v[22:23], v[176:177]
	s_nop 0
	v_exp_f32_e32 v22, v12
	v_exp_f32_e32 v23, v13
	v_fmaak_f32 v16, v14, v205, 0x3d2aaaab
	v_fmaak_f32 v19, v15, v205, 0x3d2aaaab
	v_fmaak_f32 v16, v16, v14, 0x3e2aaaab
	v_fmaak_f32 v19, v19, v15, 0x3e2aaaab
	v_fma_f32 v16, v16, v14, 0.5
	v_fma_f32 v19, v19, v15, 0.5
	v_fma_f32 v16, v16, v14, 1.0
	v_fma_f32 v19, v19, v15, 1.0
	v_mul_f32_e64 v17, v16, -v14
	v_mul_f32_e64 v12, v19, -v15
	v_fma_f32 v16, -v22, v22, 1.0
	v_cmp_lt_f32_e32 vcc, s6, v14
	v_fma_f32 v13, -v23, v23, 1.0
	s_nop 0
	v_cndmask_b32_e32 v16, v16, v17, vcc
	v_cmp_lt_f32_e32 vcc, s6, v15
	v_sqrt_f32_e32 v16, v16
	s_nop 1
	v_cndmask_b32_e32 v17, v13, v12, vcc
	v_sqrt_f32_e32 v17, v17
	s_nop 0
	v_pk_mul_f32 v[26:27], v[26:27], v[16:17]
	s_nop 0
	v_pk_mul_f32 v[26:27], v[30:31], v[26:27]
	ds_write_b128 v204, v[20:23] offset:42496
	ds_write_b128 v204, v[24:27] offset:58880
	ds_read_b128 v[12:15], v229 offset:32000
	ds_read_b128 v[16:19], v229 offset:32064
	ds_read_b128 v[28:31], v230 offset:20992
	s_waitcnt lgkmcnt(1)
; __device__ __forceinline__ float sigmoidf_(float x) { return __builtin_amdgcn_rcpf(1.0f + __expf(-x)); }
; template <bool FINAL>
; __device__ void phase_lru(const Params& p, int l, unsigned char* smem) {
;     ...
;           const int e0 = et * 16 + 4 * g, ch0 = nb * 64 + e0;
;           const float4 ba4 = *(const float4*)(p.ba + (l * 2 + d) * 512 + ch0);
;           const float4 bx4 = *(const float4*)(p.bx + (l * 2 + d) * 512 + ch0);
;           const float4 sp4 = *(const float4*)(p.SP8 + (l * 2 + d) * 512 + ch0);
;           const float4 uu = *(const float4*)(u32 + t * 64 + e0);
;           const float* bap = (const float*)&ba4; const float* bxp = (const float*)&bx4;
;           const float* spp = (const float*)&sp4; const float* uup = (const float*)&uu;
;           f32x4 av, bv;
; #pragma unroll
;           for (int j = 0; j < 4; ++j) {
;             float r = sigmoidf_(ar[j] + bap[j]);
;             float ig = sigmoidf_(ai[j] + bxp[j]);
;             float la = spp[j] * r;
;             float av_ = __expf(la);
;             float t2 = 2.0f * la;
;             float ser = -t2 * (1.f + t2 * 0.5f * (1.f + t2 * (1.f / 3.f) * (1.f + t2 * 0.25f * (1.f + t2 * 0.2f))));
;             float om = (t2 > -0.25f) ? ser : (1.0f - av_ * av_);
;             av[j] = av_;
;             bv[j] = __builtin_amdgcn_sqrtf(om) * ig * uup[j];
;           }
;           *(f32x4*)(sa + t * 64 + e0) = av;
;           *(f32x4*)(sb + t * 64 + e0) = bv;
;         }
;       }
;       __syncthreads();
;       {
;         float A = 1.f, B = 0.f;
;         if (d == 0) {
; #pragma unroll
;           for (int tt = 0; tt < 16; ++tt) { int t = qd * 16 + tt; float a = sa[t * 64 + e_], b = sb[t * 64 + e_]; B = a * B + b; A *= a; }
;         } else {
; #pragma unroll
;     ...
;         }
;         part[(0 * 4 + qd) * 64 + e_] = A;
;         part[(1 * 4 + qd) * 64 + e_] = B;
;       }
;       __syncthreads();
	v_mfma_f32_16x16x32_bf16 v[20:23], v[180:183], v[12:15], 0
	v_mfma_f32_16x16x32_bf16 v[24:27], v[188:191], v[12:15], 0
	v_mfma_f32_16x16x32_bf16 v[20:23], v[184:187], v[16:19], v[20:23]
	v_mfma_f32_16x16x32_bf16 v[24:27], v[192:195], v[16:19], v[24:27]
	s_nop 7
	s_nop 3
	s_waitcnt lgkmcnt(0)
	v_fmamk_f32 v20, v20, 0xbfb8aa3b, v196
	v_fmamk_f32 v21, v21, 0xbfb8aa3b, v197
	v_fmamk_f32 v24, v24, 0xbfb8aa3b, v200
	v_fmamk_f32 v25, v25, 0xbfb8aa3b, v201
	v_exp_f32_e32 v20, v20
	v_exp_f32_e32 v21, v21
	v_exp_f32_e32 v24, v24
	v_exp_f32_e32 v25, v25
	v_add_f32_e32 v20, 1.0, v20
	v_add_f32_e32 v21, 1.0, v21
	v_add_f32_e32 v24, 1.0, v24
	v_add_f32_e32 v25, 1.0, v25
	v_rcp_f32_e32 v20, v20
	v_rcp_f32_e32 v21, v21
	v_rcp_f32_e32 v24, v24
	v_rcp_f32_e32 v25, v25
	v_pk_mul_f32 v[14:15], v[20:21], v[170:171]
	v_pk_mul_f32 v[12:13], v[20:21], v[174:175]
	s_nop 0
	v_exp_f32_e32 v20, v12
	v_exp_f32_e32 v21, v13
	v_fmaak_f32 v16, v14, v205, 0x3d2aaaab
	v_fmaak_f32 v19, v15, v205, 0x3d2aaaab
	v_fmaak_f32 v16, v16, v14, 0x3e2aaaab
	v_fmaak_f32 v19, v19, v15, 0x3e2aaaab
	v_fma_f32 v16, v16, v14, 0.5
	v_fma_f32 v19, v19, v15, 0.5
	v_fma_f32 v16, v16, v14, 1.0
	v_fma_f32 v19, v19, v15, 1.0
	v_mul_f32_e64 v17, v16, -v14
	v_mul_f32_e64 v12, v19, -v15
	v_fma_f32 v16, -v20, v20, 1.0
	v_cmp_lt_f32_e32 vcc, s6, v14
	v_fma_f32 v13, -v21, v21, 1.0
	s_nop 0
	v_cndmask_b32_e32 v16, v16, v17, vcc
	v_cmp_lt_f32_e32 vcc, s6, v15
	v_sqrt_f32_e32 v16, v16
	s_nop 1
	v_cndmask_b32_e32 v17, v13, v12, vcc
	v_sqrt_f32_e32 v17, v17
	s_nop 0
	v_pk_mul_f32 v[24:25], v[24:25], v[16:17]
	s_nop 0
	v_pk_mul_f32 v[24:25], v[28:29], v[24:25]
	v_fmamk_f32 v22, v22, 0xbfb8aa3b, v198
	v_fmamk_f32 v23, v23, 0xbfb8aa3b, v199
	v_fmamk_f32 v26, v26, 0xbfb8aa3b, v202
	v_fmamk_f32 v27, v27, 0xbfb8aa3b, v203
	v_exp_f32_e32 v22, v22
	v_exp_f32_e32 v23, v23
	v_exp_f32_e32 v26, v26
	v_exp_f32_e32 v27, v27
	v_add_f32_e32 v22, 1.0, v22
	v_add_f32_e32 v23, 1.0, v23
	v_add_f32_e32 v26, 1.0, v26
	v_add_f32_e32 v27, 1.0, v27
	v_rcp_f32_e32 v22, v22
	v_rcp_f32_e32 v23, v23
	v_rcp_f32_e32 v26, v26
	v_rcp_f32_e32 v27, v27
	v_pk_mul_f32 v[14:15], v[22:23], v[172:173]
	v_pk_mul_f32 v[12:13], v[22:23], v[176:177]
	s_nop 0
	v_exp_f32_e32 v22, v12
	v_exp_f32_e32 v23, v13
	v_fmaak_f32 v16, v14, v205, 0x3d2aaaab
	v_fmaak_f32 v19, v15, v205, 0x3d2aaaab
	v_fmaak_f32 v16, v16, v14, 0x3e2aaaab
	v_fmaak_f32 v19, v19, v15, 0x3e2aaaab
	v_fma_f32 v16, v16, v14, 0.5
	v_fma_f32 v19, v19, v15, 0.5
	v_fma_f32 v16, v16, v14, 1.0
	v_fma_f32 v19, v19, v15, 1.0
	v_mul_f32_e64 v17, v16, -v14
	v_mul_f32_e64 v12, v19, -v15
	v_fma_f32 v16, -v22, v22, 1.0
	v_cmp_lt_f32_e32 vcc, s6, v14
	v_fma_f32 v13, -v23, v23, 1.0
	s_nop 0
	v_cndmask_b32_e32 v16, v16, v17, vcc
	v_cmp_lt_f32_e32 vcc, s6, v15
	v_sqrt_f32_e32 v16, v16
	s_nop 1
	v_cndmask_b32_e32 v17, v13, v12, vcc
	v_sqrt_f32_e32 v17, v17
	s_nop 0
	v_pk_mul_f32 v[26:27], v[26:27], v[16:17]
	s_nop 0
	v_pk_mul_f32 v[26:27], v[30:31], v[26:27]
	ds_write_b128 v204, v[20:23] offset:46592
	ds_write_b128 v204, v[24:27] offset:62976
	s_waitcnt lgkmcnt(0)
	s_barrier
	ds_read2st64_b32 v[12:13], v59 offset0:134 offset1:198
	ds_read2st64_b32 v[14:15], v118 offset0:134 offset1:198
	ds_read2st64_b32 v[16:17], v119 offset0:134 offset1:198
	ds_read2st64_b32 v[64:65], v129 offset0:134 offset1:198
	ds_read2st64_b32 v[66:67], v130 offset0:134 offset1:198
	s_waitcnt lgkmcnt(4)
	v_fmac_f32_e32 v13, 0, v12
	s_waitcnt lgkmcnt(3)
	v_mul_f32_e32 v18, v12, v14
	s_waitcnt lgkmcnt(2)
	v_mul_f32_e32 v20, v18, v16
	ds_read2st64_b32 v[18:19], v120 offset0:134 offset1:198
	v_fmac_f32_e32 v15, v14, v13
	v_fmac_f32_e32 v17, v16, v15
	ds_read2st64_b32 v[68:69], v131 offset0:134 offset1:198
	ds_read2st64_b32 v[70:71], v132 offset0:134 offset1:198
	s_waitcnt lgkmcnt(2)
	v_mul_f32_e32 v22, v20, v18
	ds_read2st64_b32 v[20:21], v121 offset0:134 offset1:198
	v_fmac_f32_e32 v19, v18, v17
	s_waitcnt lgkmcnt(0)
	v_mul_f32_e32 v24, v22, v20
	ds_read2st64_b32 v[22:23], v122 offset0:134 offset1:198
	v_fmac_f32_e32 v21, v20, v19
	s_waitcnt lgkmcnt(0)
	v_mul_f32_e32 v26, v24, v22
	ds_read2st64_b32 v[24:25], v123 offset0:134 offset1:198
	v_fmac_f32_e32 v23, v22, v21
	s_waitcnt lgkmcnt(0)
	v_mul_f32_e32 v28, v26, v24
	ds_read2st64_b32 v[26:27], v124 offset0:134 offset1:198
	v_fmac_f32_e32 v25, v24, v23
	s_waitcnt lgkmcnt(0)
	v_mul_f32_e32 v30, v28, v26
	ds_read2st64_b32 v[28:29], v125 offset0:134 offset1:198
	v_fmac_f32_e32 v27, v26, v25
	s_waitcnt lgkmcnt(0)
	v_mul_f32_e32 v32, v30, v28
	ds_read2st64_b32 v[30:31], v126 offset0:134 offset1:198
	v_fmac_f32_e32 v29, v28, v27
	s_waitcnt lgkmcnt(0)
	v_mul_f32_e32 v34, v32, v30
	ds_read2st64_b32 v[32:33], v127 offset0:134 offset1:198
	v_fmac_f32_e32 v31, v30, v29
	s_waitcnt lgkmcnt(0)
	v_mul_f32_e32 v63, v34, v32
	ds_read2st64_b32 v[34:35], v128 offset0:134 offset1:198
	v_fmac_f32_e32 v33, v32, v31
	s_waitcnt lgkmcnt(0)
	v_mul_f32_e32 v63, v63, v34
	v_mul_f32_e32 v63, v63, v64
	v_fmac_f32_e32 v35, v34, v33
	v_mul_f32_e32 v63, v63, v66
	v_fmac_f32_e32 v65, v64, v35
	v_mul_f32_e32 v63, v63, v68
	v_fmac_f32_e32 v67, v66, v65
	v_mul_f32_e32 v63, v63, v70
	v_fmac_f32_e32 v69, v68, v67
	v_fmac_f32_e32 v71, v70, v69
	ds_write_b32 v98, v63
	ds_write_b32 v100, v71 offset:1024
	s_waitcnt lgkmcnt(0)
	s_barrier
	s_and_saveexec_b64 s[56:57], s[22:23]
	s_cbranch_execnz .LBB0_218
	s_or_b64 exec, exec, s[56:57]
	s_and_saveexec_b64 s[56:57], s[24:25]
	s_cbranch_execnz .LBB0_219

; template <bool FINAL>
; __device__ void phase_lru(const Params& p, int l, unsigned char* smem) {
;     ...
;     for (int d = 0; d < 2; ++d) {
;       {
;         bf16x8 uf[2];
;         uf[0] = *(const bf16x8*)(ub + (16 * w + l15) * 72 + g * 8);
;         uf[1] = *(const bf16x8*)(ub + (16 * w + l15) * 72 + 32 + g * 8);
;         const int t = 16 * w + l15;
; #pragma unroll
;         for (int et = 0; et < 4; ++et) {
;           f32x4 ar = {0.f, 0.f, 0.f, 0.f}, ai = {0.f, 0.f, 0.f, 0.f};
;           const u16* wr = p.WLRU + ((((size_t)(l * 2 + d) * 2 + 0) * 8 + nb) * 64 + et * 16 + l15) * 64 + g * 8;
;           const u16* wi = p.WLRU + ((((size_t)(l * 2 + d) * 2 + 1) * 8 + nb) * 64 + et * 16 + l15) * 64 + g * 8;
; #pragma unroll
;           for (int ks = 0; ks < 2; ++ks) {
;             ar = mfma16(*(const bf16x8*)(wr + ks * 32), uf[ks], ar);
;             ai = mfma16(*(const bf16x8*)(wi + ks * 32), uf[ks], ai);
;           }
;           const int e0 = et * 16 + 4 * g, ch0 = nb * 64 + e0;
;           const float4 ba4 = *(const float4*)(p.ba + (l * 2 + d) * 512 + ch0);
;           const float4 bx4 = *(const float4*)(p.bx + (l * 2 + d) * 512 + ch0);
;           const float4 sp4 = *(const float4*)(p.SP8 + (l * 2 + d) * 512 + ch0);
;           const float4 uu = *(const float4*)(u32 + t * 64 + e0);
;           const float* bap = (const float*)&ba4; const float* bxp = (const float*)&bx4;
;           const float* spp = (const float*)&sp4; const float* uup = (const float*)&uu;
;           f32x4 av, bv;
; #pragma unroll
;           for (int j = 0; j < 4; ++j) {
;             float r = sigmoidf_(ar[j] + bap[j]);
;             float ig = sigmoidf_(ai[j] + bxp[j]);
;             float la = spp[j] * r;
;             float av_ = __expf(la);
;             float t2 = 2.0f * la;
;             float ser = -t2 * (1.f + t2 * 0.5f * (1.f + t2 * (1.f / 3.f) * (1.f + t2 * 0.25f * (1.f + t2 * 0.2f))));
;             float om = (t2 > -0.25f) ? ser : (1.0f - av_ * av_);
;             av[j] = av_;
;             bv[j] = __builtin_amdgcn_sqrtf(om) * ig * uup[j];
;           }
;           *(f32x4*)(sa + t * 64 + e0) = av;
;           *(f32x4*)(sb + t * 64 + e0) = bv;
;         }
;     ...
;           for (int tt = 0; tt < 16; ++tt) { int t = qd * 16 + tt; h = sa[t * 64 + e_] * h + sb[t * 64 + e_]; hsum[tt] += h; }
.LBB0_214:
	s_or_b64 exec, exec, s[56:57]
	v_lshl_add_u64 v[20:21], s[64:65], 0, v[144:145]
	v_mov_b32_e32 v63, v145
	v_lshl_add_u64 v[28:29], v[20:21], 0, v[62:63]
	ds_read2st64_b32 v[94:95], v59 offset0:134 offset1:198
	ds_read2st64_b32 v[92:93], v118 offset0:134 offset1:198
	ds_read2st64_b32 v[90:91], v119 offset0:134 offset1:198
	ds_read2st64_b32 v[88:89], v120 offset0:134 offset1:198
	ds_read2st64_b32 v[86:87], v121 offset0:134 offset1:198
	ds_read2st64_b32 v[84:85], v122 offset0:134 offset1:198
	ds_read2st64_b32 v[82:83], v123 offset0:134 offset1:198
	ds_read2st64_b32 v[80:81], v124 offset0:134 offset1:198
	ds_read2st64_b32 v[78:79], v125 offset0:134 offset1:198
	ds_read2st64_b32 v[76:77], v126 offset0:134 offset1:198
	ds_read2st64_b32 v[74:75], v127 offset0:134 offset1:198
	ds_read2st64_b32 v[72:73], v128 offset0:134 offset1:198
	ds_read2st64_b32 v[70:71], v129 offset0:134 offset1:198
	ds_read2st64_b32 v[68:69], v130 offset0:134 offset1:198
	ds_read2st64_b32 v[64:65], v131 offset0:134 offset1:198
	ds_read2st64_b32 v[66:67], v132 offset0:134 offset1:198
	s_waitcnt lgkmcnt(0)
	s_barrier
	s_mov_b32 s5, 0x3e4ccccd
	global_load_dwordx4 v[196:199], v231, s[66:67]
	global_load_dwordx4 v[200:203], v231, s[68:69]
	global_load_dwordx4 v[32:35], v231, s[72:73]
	ds_read_b128 v[12:15], v229 offset:25088
	ds_read_b128 v[16:19], v229 offset:25152
	ds_read_b128 v[28:31], v230 offset:8704
	s_waitcnt lgkmcnt(1)
	v_mfma_f32_16x16x32_bf16 v[20:23], v[232:235], v[12:15], 0
	v_mfma_f32_16x16x32_bf16 v[24:27], v[240:243], v[12:15], 0
	v_mfma_f32_16x16x32_bf16 v[20:23], v[236:239], v[16:19], v[20:23]
	v_mfma_f32_16x16x32_bf16 v[24:27], v[244:247], v[16:19], v[24:27]
	s_waitcnt vmcnt(0)
	v_mul_f32_e32 v196, 0xbfb8aa3b, v196
	v_mul_f32_e32 v197, 0xbfb8aa3b, v197
	v_mul_f32_e32 v198, 0xbfb8aa3b, v198
	v_mul_f32_e32 v199, 0xbfb8aa3b, v199
	v_mul_f32_e32 v200, 0xbfb8aa3b, v200
	v_mul_f32_e32 v201, 0xbfb8aa3b, v201
	v_mul_f32_e32 v202, 0xbfb8aa3b, v202
	v_mul_f32_e32 v203, 0xbfb8aa3b, v203
	v_add_f32_e32 v170, v32, v32
	v_add_f32_e32 v171, v33, v33
	v_add_f32_e32 v172, v34, v34
	v_add_f32_e32 v173, v35, v35
	v_mul_f32_e32 v174, 0x3fb8aa3b, v32
	v_mul_f32_e32 v175, 0x3fb8aa3b, v33
	v_mul_f32_e32 v176, 0x3fb8aa3b, v34
	v_mul_f32_e32 v177, 0x3fb8aa3b, v35
	s_nop 7
	s_nop 3
	s_waitcnt lgkmcnt(0)
	v_fmamk_f32 v20, v20, 0xbfb8aa3b, v196
	v_fmamk_f32 v21, v21, 0xbfb8aa3b, v197
	v_fmamk_f32 v24, v24, 0xbfb8aa3b, v200
	v_fmamk_f32 v25, v25, 0xbfb8aa3b, v201
	v_exp_f32_e32 v20, v20
	v_exp_f32_e32 v21, v21
	v_exp_f32_e32 v24, v24
	v_exp_f32_e32 v25, v25
	v_add_f32_e32 v20, 1.0, v20
	v_add_f32_e32 v21, 1.0, v21
	v_add_f32_e32 v24, 1.0, v24
	v_add_f32_e32 v25, 1.0, v25
	v_rcp_f32_e32 v20, v20
	v_rcp_f32_e32 v21, v21
	v_rcp_f32_e32 v24, v24
	v_rcp_f32_e32 v25, v25
	v_pk_mul_f32 v[14:15], v[20:21], v[170:171]
	v_pk_mul_f32 v[12:13], v[20:21], v[174:175]
	s_nop 0
	v_exp_f32_e32 v20, v12
	v_exp_f32_e32 v21, v13
	v_fmaak_f32 v16, v14, v205, 0x3d2aaaab
	v_fmaak_f32 v19, v15, v205, 0x3d2aaaab
	v_fmaak_f32 v16, v16, v14, 0x3e2aaaab
	v_fmaak_f32 v19, v19, v15, 0x3e2aaaab
	v_fma_f32 v16, v16, v14, 0.5
	v_fma_f32 v19, v19, v15, 0.5
	v_fma_f32 v16, v16, v14, 1.0
	v_fma_f32 v19, v19, v15, 1.0
	v_mul_f32_e64 v17, v16, -v14
	v_mul_f32_e64 v12, v19, -v15
	v_fma_f32 v16, -v20, v20, 1.0
	v_cmp_lt_f32_e32 vcc, s6, v14
	v_fma_f32 v13, -v21, v21, 1.0
	s_nop 0
	v_cndmask_b32_e32 v16, v16, v17, vcc
	v_cmp_lt_f32_e32 vcc, s6, v15
	v_sqrt_f32_e32 v16, v16
	s_nop 1
	v_cndmask_b32_e32 v17, v13, v12, vcc
	v_sqrt_f32_e32 v17, v17
	s_nop 0
	v_pk_mul_f32 v[24:25], v[24:25], v[16:17]
	s_nop 0
	v_pk_mul_f32 v[24:25], v[28:29], v[24:25]
	v_fmamk_f32 v22, v22, 0xbfb8aa3b, v198
	v_fmamk_f32 v23, v23, 0xbfb8aa3b, v199
	v_fmamk_f32 v26, v26, 0xbfb8aa3b, v202
	v_fmamk_f32 v27, v27, 0xbfb8aa3b, v203
	v_exp_f32_e32 v22, v22
	v_exp_f32_e32 v23, v23
	v_exp_f32_e32 v26, v26
	v_exp_f32_e32 v27, v27
	v_add_f32_e32 v22, 1.0, v22
	v_add_f32_e32 v23, 1.0, v23
	v_add_f32_e32 v26, 1.0, v26
	v_add_f32_e32 v27, 1.0, v27
	v_rcp_f32_e32 v22, v22
	v_rcp_f32_e32 v23, v23
	v_rcp_f32_e32 v26, v26
	v_rcp_f32_e32 v27, v27
	v_pk_mul_f32 v[14:15], v[22:23], v[172:173]
	v_pk_mul_f32 v[12:13], v[22:23], v[176:177]
	s_nop 0
	v_exp_f32_e32 v22, v12
	v_exp_f32_e32 v23, v13
	v_fmaak_f32 v16, v14, v205, 0x3d2aaaab
	v_fmaak_f32 v19, v15, v205, 0x3d2aaaab
	v_fmaak_f32 v16, v16, v14, 0x3e2aaaab
	v_fmaak_f32 v19, v19, v15, 0x3e2aaaab
	v_fma_f32 v16, v16, v14, 0.5
	v_fma_f32 v19, v19, v15, 0.5
	v_fma_f32 v16, v16, v14, 1.0
	v_fma_f32 v19, v19, v15, 1.0
	v_mul_f32_e64 v17, v16, -v14
	v_mul_f32_e64 v12, v19, -v15
	v_fma_f32 v16, -v22, v22, 1.0
	v_cmp_lt_f32_e32 vcc, s6, v14
	v_fma_f32 v13, -v23, v23, 1.0
	s_nop 0
	v_cndmask_b32_e32 v16, v16, v17, vcc
	v_cmp_lt_f32_e32 vcc, s6, v15
	v_sqrt_f32_e32 v16, v16
	s_nop 1
	v_cndmask_b32_e32 v17, v13, v12, vcc
	v_sqrt_f32_e32 v17, v17
	s_nop 0
	v_pk_mul_f32 v[26:27], v[26:27], v[16:17]
	s_nop 0
	v_pk_mul_f32 v[26:27], v[30:31], v[26:27]
	ds_write_b128 v204, v[20:23] offset:34304
	ds_write_b128 v204, v[24:27] offset:50688
	ds_read_b128 v[12:15], v229 offset:27392
	ds_read_b128 v[16:19], v229 offset:27456
	ds_read_b128 v[28:31], v230 offset:12800
	s_waitcnt lgkmcnt(1)
	v_mfma_f32_16x16x32_bf16 v[20:23], v[232:235], v[12:15], 0
	v_mfma_f32_16x16x32_bf16 v[24:27], v[240:243], v[12:15], 0
	v_mfma_f32_16x16x32_bf16 v[20:23], v[236:239], v[16:19], v[20:23]
	v_mfma_f32_16x16x32_bf16 v[24:27], v[244:247], v[16:19], v[24:27]
	s_nop 7
	s_nop 3
	s_waitcnt lgkmcnt(0)
; __device__ __forceinline__ float sigmoidf_(float x) { return __builtin_amdgcn_rcpf(1.0f + __expf(-x)); }
; template <bool FINAL>
; __device__ void phase_lru(const Params& p, int l, unsigned char* smem) {
;     ...
;           const int e0 = et * 16 + 4 * g, ch0 = nb * 64 + e0;
;           const float4 ba4 = *(const float4*)(p.ba + (l * 2 + d) * 512 + ch0);
;           const float4 bx4 = *(const float4*)(p.bx + (l * 2 + d) * 512 + ch0);
;           const float4 sp4 = *(const float4*)(p.SP8 + (l * 2 + d) * 512 + ch0);
;           const float4 uu = *(const float4*)(u32 + t * 64 + e0);
;           const float* bap = (const float*)&ba4; const float* bxp = (const float*)&bx4;
;           const float* spp = (const float*)&sp4; const float* uup = (const float*)&uu;
;           f32x4 av, bv;
; #pragma unroll
;           for (int j = 0; j < 4; ++j) {
;             float r = sigmoidf_(ar[j] + bap[j]);
;             float ig = sigmoidf_(ai[j] + bxp[j]);
;             float la = spp[j] * r;
;             float av_ = __expf(la);
;             float t2 = 2.0f * la;
;             float ser = -t2 * (1.f + t2 * 0.5f * (1.f + t2 * (1.f / 3.f) * (1.f + t2 * 0.25f * (1.f + t2 * 0.2f))));
;             float om = (t2 > -0.25f) ? ser : (1.0f - av_ * av_);
;             av[j] = av_;
;             bv[j] = __builtin_amdgcn_sqrtf(om) * ig * uup[j];
;           }
;           *(f32x4*)(sa + t * 64 + e0) = av;
;           *(f32x4*)(sb + t * 64 + e0) = bv;
;         }
	v_fmamk_f32 v20, v20, 0xbfb8aa3b, v196
	v_fmamk_f32 v21, v21, 0xbfb8aa3b, v197
	v_fmamk_f32 v24, v24, 0xbfb8aa3b, v200
	v_fmamk_f32 v25, v25, 0xbfb8aa3b, v201
	v_exp_f32_e32 v20, v20
	v_exp_f32_e32 v21, v21
	v_exp_f32_e32 v24, v24
	v_exp_f32_e32 v25, v25
	v_add_f32_e32 v20, 1.0, v20
	v_add_f32_e32 v21, 1.0, v21
	v_add_f32_e32 v24, 1.0, v24
	v_add_f32_e32 v25, 1.0, v25
	v_rcp_f32_e32 v20, v20
	v_rcp_f32_e32 v21, v21
	v_rcp_f32_e32 v24, v24
	v_rcp_f32_e32 v25, v25
	v_pk_mul_f32 v[14:15], v[20:21], v[170:171]
	v_pk_mul_f32 v[12:13], v[20:21], v[174:175]
	s_nop 0
	v_exp_f32_e32 v20, v12
	v_exp_f32_e32 v21, v13
	v_fmaak_f32 v16, v14, v205, 0x3d2aaaab
	v_fmaak_f32 v19, v15, v205, 0x3d2aaaab
	v_fmaak_f32 v16, v16, v14, 0x3e2aaaab
	v_fmaak_f32 v19, v19, v15, 0x3e2aaaab
	v_fma_f32 v16, v16, v14, 0.5
	v_fma_f32 v19, v19, v15, 0.5
	v_fma_f32 v16, v16, v14, 1.0
	v_fma_f32 v19, v19, v15, 1.0
	v_mul_f32_e64 v17, v16, -v14
	v_mul_f32_e64 v12, v19, -v15
	v_fma_f32 v16, -v20, v20, 1.0
	v_cmp_lt_f32_e32 vcc, s6, v14
	v_fma_f32 v13, -v21, v21, 1.0
	s_nop 0
	v_cndmask_b32_e32 v16, v16, v17, vcc
	v_cmp_lt_f32_e32 vcc, s6, v15
	v_sqrt_f32_e32 v16, v16
	s_nop 1
	v_cndmask_b32_e32 v17, v13, v12, vcc
	v_sqrt_f32_e32 v17, v17
	s_nop 0
	v_pk_mul_f32 v[24:25], v[24:25], v[16:17]
	s_nop 0
	v_pk_mul_f32 v[24:25], v[28:29], v[24:25]
	v_fmamk_f32 v22, v22, 0xbfb8aa3b, v198
	v_fmamk_f32 v23, v23, 0xbfb8aa3b, v199
	v_fmamk_f32 v26, v26, 0xbfb8aa3b, v202
	v_fmamk_f32 v27, v27, 0xbfb8aa3b, v203
	v_exp_f32_e32 v22, v22
	v_exp_f32_e32 v23, v23
	v_exp_f32_e32 v26, v26
	v_exp_f32_e32 v27, v27
	v_add_f32_e32 v22, 1.0, v22
	v_add_f32_e32 v23, 1.0, v23
	v_add_f32_e32 v26, 1.0, v26
	v_add_f32_e32 v27, 1.0, v27
	v_rcp_f32_e32 v22, v22
	v_rcp_f32_e32 v23, v23
	v_rcp_f32_e32 v26, v26
	v_rcp_f32_e32 v27, v27
	v_pk_mul_f32 v[14:15], v[22:23], v[172:173]
	v_pk_mul_f32 v[12:13], v[22:23], v[176:177]
	s_nop 0
	v_exp_f32_e32 v22, v12
	v_exp_f32_e32 v23, v13
	v_fmaak_f32 v16, v14, v205, 0x3d2aaaab
	v_fmaak_f32 v19, v15, v205, 0x3d2aaaab
	v_fmaak_f32 v16, v16, v14, 0x3e2aaaab
	v_fmaak_f32 v19, v19, v15, 0x3e2aaaab
	v_fma_f32 v16, v16, v14, 0.5
	v_fma_f32 v19, v19, v15, 0.5
	v_fma_f32 v16, v16, v14, 1.0
	v_fma_f32 v19, v19, v15, 1.0
	v_mul_f32_e64 v17, v16, -v14
	v_mul_f32_e64 v12, v19, -v15
	v_fma_f32 v16, -v22, v22, 1.0
	v_cmp_lt_f32_e32 vcc, s6, v14
	v_fma_f32 v13, -v23, v23, 1.0
	s_nop 0
	v_cndmask_b32_e32 v16, v16, v17, vcc
	v_cmp_lt_f32_e32 vcc, s6, v15
	v_sqrt_f32_e32 v16, v16
	s_nop 1
	v_cndmask_b32_e32 v17, v13, v12, vcc
	v_sqrt_f32_e32 v17, v17
	s_nop 0
	v_pk_mul_f32 v[26:27], v[26:27], v[16:17]
	s_nop 0
	v_pk_mul_f32 v[26:27], v[30:31], v[26:27]
	ds_write_b128 v204, v[20:23] offset:38400
	ds_write_b128 v204, v[24:27] offset:54784
	ds_read_b128 v[12:15], v229 offset:29696
	ds_read_b128 v[16:19], v229 offset:29760
	ds_read_b128 v[28:31], v230 offset:16896
	s_waitcnt lgkmcnt(1)
	v_mfma_f32_16x16x32_bf16 v[20:23], v[232:235], v[12:15], 0
	v_mfma_f32_16x16x32_bf16 v[24:27], v[240:243], v[12:15], 0
	v_mfma_f32_16x16x32_bf16 v[20:23], v[236:239], v[16:19], v[20:23]
	v_mfma_f32_16x16x32_bf16 v[24:27], v[244:247], v[16:19], v[24:27]
	s_nop 7
	s_nop 3
	s_waitcnt lgkmcnt(0)
	v_fmamk_f32 v20, v20, 0xbfb8aa3b, v196
	v_fmamk_f32 v21, v21, 0xbfb8aa3b, v197
	v_fmamk_f32 v24, v24, 0xbfb8aa3b, v200
	v_fmamk_f32 v25, v25, 0xbfb8aa3b, v201
	v_exp_f32_e32 v20, v20
	v_exp_f32_e32 v21, v21
	v_exp_f32_e32 v24, v24
	v_exp_f32_e32 v25, v25
	v_add_f32_e32 v20, 1.0, v20
	v_add_f32_e32 v21, 1.0, v21
	v_add_f32_e32 v24, 1.0, v24
	v_add_f32_e32 v25, 1.0, v25
	v_rcp_f32_e32 v20, v20
	v_rcp_f32_e32 v21, v21
	v_rcp_f32_e32 v24, v24
	v_rcp_f32_e32 v25, v25
	v_pk_mul_f32 v[14:15], v[20:21], v[170:171]
	v_pk_mul_f32 v[12:13], v[20:21], v[174:175]
	s_nop 0
	v_exp_f32_e32 v20, v12
	v_exp_f32_e32 v21, v13
	v_fmaak_f32 v16, v14, v205, 0x3d2aaaab
	v_fmaak_f32 v19, v15, v205, 0x3d2aaaab
	v_fmaak_f32 v16, v16, v14, 0x3e2aaaab
	v_fmaak_f32 v19, v19, v15, 0x3e2aaaab
	v_fma_f32 v16, v16, v14, 0.5
	v_fma_f32 v19, v19, v15, 0.5
	v_fma_f32 v16, v16, v14, 1.0
	v_fma_f32 v19, v19, v15, 1.0
	v_mul_f32_e64 v17, v16, -v14
	v_mul_f32_e64 v12, v19, -v15
	v_fma_f32 v16, -v20, v20, 1.0
	v_cmp_lt_f32_e32 vcc, s6, v14
	v_fma_f32 v13, -v21, v21, 1.0
	s_nop 0
	v_cndmask_b32_e32 v16, v16, v17, vcc
	v_cmp_lt_f32_e32 vcc, s6, v15
	v_sqrt_f32_e32 v16, v16
	s_nop 1
	v_cndmask_b32_e32 v17, v13, v12, vcc
	v_sqrt_f32_e32 v17, v17
	s_nop 0
	v_pk_mul_f32 v[24:25], v[24:25], v[16:17]
	s_nop 0
	v_pk_mul_f32 v[24:25], v[28:29], v[24:25]
	v_fmamk_f32 v22, v22, 0xbfb8aa3b, v198
	v_fmamk_f32 v23, v23, 0xbfb8aa3b, v199
	v_fmamk_f32 v26, v26, 0xbfb8aa3b, v202
	v_fmamk_f32 v27, v27, 0xbfb8aa3b, v203
	v_exp_f32_e32 v22, v22
	v_exp_f32_e32 v23, v23
	v_exp_f32_e32 v26, v26
	v_exp_f32_e32 v27, v27
	v_add_f32_e32 v22, 1.0, v22
	v_add_f32_e32 v23, 1.0, v23
	v_add_f32_e32 v26, 1.0, v26
	v_add_f32_e32 v27, 1.0, v27
	v_rcp_f32_e32 v22, v22
	v_rcp_f32_e32 v23, v23
	v_rcp_f32_e32 v26, v26
	v_rcp_f32_e32 v27, v27
	v_pk_mul_f32 v[14:15], v[22:23], v[172:173]
	v_pk_mul_f32 v[12:13], v[22:23], v[176:177]
	s_nop 0
	v_exp_f32_e32 v22, v12
	v_exp_f32_e32 v23, v13
	v_fmaak_f32 v16, v14, v205, 0x3d2aaaab
	v_fmaak_f32 v19, v15, v205, 0x3d2aaaab
	v_fmaak_f32 v16, v16, v14, 0x3e2aaaab
	v_fmaak_f32 v19, v19, v15, 0x3e2aaaab
	v_fma_f32 v16, v16, v14, 0.5
	v_fma_f32 v19, v19, v15, 0.5
	v_fma_f32 v16, v16, v14, 1.0
	v_fma_f32 v19, v19, v15, 1.0
	v_mul_f32_e64 v17, v16, -v14
	v_mul_f32_e64 v12, v19, -v15
	v_fma_f32 v16, -v22, v22, 1.0
	v_cmp_lt_f32_e32 vcc, s6, v14
	v_fma_f32 v13, -v23, v23, 1.0
	s_nop 0
	v_cndmask_b32_e32 v16, v16, v17, vcc
	v_cmp_lt_f32_e32 vcc, s6, v15
	v_sqrt_f32_e32 v16, v16
	s_nop 1
	v_cndmask_b32_e32 v17, v13, v12, vcc
	v_sqrt_f32_e32 v17, v17
	s_nop 0
	v_pk_mul_f32 v[26:27], v[26:27], v[16:17]
	s_nop 0
	v_pk_mul_f32 v[26:27], v[30:31], v[26:27]
	ds_write_b128 v204, v[20:23] offset:42496
	ds_write_b128 v204, v[24:27] offset:58880
	ds_read_b128 v[12:15], v229 offset:32000
	ds_read_b128 v[16:19], v229 offset:32064
	ds_read_b128 v[28:31], v230 offset:20992
	s_waitcnt lgkmcnt(1)
; __device__ __forceinline__ float sigmoidf_(float x) { return __builtin_amdgcn_rcpf(1.0f + __expf(-x)); }
; template <bool FINAL>
; __device__ void phase_lru(const Params& p, int l, unsigned char* smem) {
;     ...
;           const int e0 = et * 16 + 4 * g, ch0 = nb * 64 + e0;
;           const float4 ba4 = *(const float4*)(p.ba + (l * 2 + d) * 512 + ch0);
;           const float4 bx4 = *(const float4*)(p.bx + (l * 2 + d) * 512 + ch0);
;           const float4 sp4 = *(const float4*)(p.SP8 + (l * 2 + d) * 512 + ch0);
;           const float4 uu = *(const float4*)(u32 + t * 64 + e0);
;           const float* bap = (const float*)&ba4; const float* bxp = (const float*)&bx4;
;           const float* spp = (const float*)&sp4; const float* uup = (const float*)&uu;
;           f32x4 av, bv;
; #pragma unroll
;           for (int j = 0; j < 4; ++j) {
;             float r = sigmoidf_(ar[j] + bap[j]);
;             float ig = sigmoidf_(ai[j] + bxp[j]);
;             float la = spp[j] * r;
;             float av_ = __expf(la);
;             float t2 = 2.0f * la;
;             float ser = -t2 * (1.f + t2 * 0.5f * (1.f + t2 * (1.f / 3.f) * (1.f + t2 * 0.25f * (1.f + t2 * 0.2f))));
;             float om = (t2 > -0.25f) ? ser : (1.0f - av_ * av_);
;             av[j] = av_;
;             bv[j] = __builtin_amdgcn_sqrtf(om) * ig * uup[j];
;           }
;           *(f32x4*)(sa + t * 64 + e0) = av;
;           *(f32x4*)(sb + t * 64 + e0) = bv;
;         }
;       }
;       __syncthreads();
;       {
;         float A = 1.f, B = 0.f;
;         if (d == 0) {
; #pragma unroll
;           for (int tt = 0; tt < 16; ++tt) { int t = qd * 16 + tt; float a = sa[t * 64 + e_], b = sb[t * 64 + e_]; B = a * B + b; A *= a; }
;         } else {
; #pragma unroll
;     ...
;         }
;         part[(0 * 4 + qd) * 64 + e_] = A;
;         part[(1 * 4 + qd) * 64 + e_] = B;
;       }
;       __syncthreads();
	v_mfma_f32_16x16x32_bf16 v[20:23], v[232:235], v[12:15], 0
	v_mfma_f32_16x16x32_bf16 v[24:27], v[240:243], v[12:15], 0
	v_mfma_f32_16x16x32_bf16 v[20:23], v[236:239], v[16:19], v[20:23]
	v_mfma_f32_16x16x32_bf16 v[24:27], v[244:247], v[16:19], v[24:27]
	s_nop 7
	s_nop 3
	s_waitcnt lgkmcnt(0)
	v_fmamk_f32 v20, v20, 0xbfb8aa3b, v196
	v_fmamk_f32 v21, v21, 0xbfb8aa3b, v197
	v_fmamk_f32 v24, v24, 0xbfb8aa3b, v200
	v_fmamk_f32 v25, v25, 0xbfb8aa3b, v201
	v_exp_f32_e32 v20, v20
	v_exp_f32_e32 v21, v21
	v_exp_f32_e32 v24, v24
	v_exp_f32_e32 v25, v25
	v_add_f32_e32 v20, 1.0, v20
	v_add_f32_e32 v21, 1.0, v21
	v_add_f32_e32 v24, 1.0, v24
	v_add_f32_e32 v25, 1.0, v25
	v_rcp_f32_e32 v20, v20
	v_rcp_f32_e32 v21, v21
	v_rcp_f32_e32 v24, v24
	v_rcp_f32_e32 v25, v25
	v_pk_mul_f32 v[14:15], v[20:21], v[170:171]
	v_pk_mul_f32 v[12:13], v[20:21], v[174:175]
	s_nop 0
	v_exp_f32_e32 v20, v12
	v_exp_f32_e32 v21, v13
	v_fmaak_f32 v16, v14, v205, 0x3d2aaaab
	v_fmaak_f32 v19, v15, v205, 0x3d2aaaab
	v_fmaak_f32 v16, v16, v14, 0x3e2aaaab
	v_fmaak_f32 v19, v19, v15, 0x3e2aaaab
	v_fma_f32 v16, v16, v14, 0.5
	v_fma_f32 v19, v19, v15, 0.5
	v_fma_f32 v16, v16, v14, 1.0
	v_fma_f32 v19, v19, v15, 1.0
	v_mul_f32_e64 v17, v16, -v14
	v_mul_f32_e64 v12, v19, -v15
	v_fma_f32 v16, -v20, v20, 1.0
	v_cmp_lt_f32_e32 vcc, s6, v14
	v_fma_f32 v13, -v21, v21, 1.0
	s_nop 0
	v_cndmask_b32_e32 v16, v16, v17, vcc
	v_cmp_lt_f32_e32 vcc, s6, v15
	v_sqrt_f32_e32 v16, v16
	s_nop 1
	v_cndmask_b32_e32 v17, v13, v12, vcc
	v_sqrt_f32_e32 v17, v17
	s_nop 0
	v_pk_mul_f32 v[24:25], v[24:25], v[16:17]
	s_nop 0
	v_pk_mul_f32 v[24:25], v[28:29], v[24:25]
	v_fmamk_f32 v22, v22, 0xbfb8aa3b, v198
	v_fmamk_f32 v23, v23, 0xbfb8aa3b, v199
	v_fmamk_f32 v26, v26, 0xbfb8aa3b, v202
	v_fmamk_f32 v27, v27, 0xbfb8aa3b, v203
	v_exp_f32_e32 v22, v22
	v_exp_f32_e32 v23, v23
	v_exp_f32_e32 v26, v26
	v_exp_f32_e32 v27, v27
	v_add_f32_e32 v22, 1.0, v22
	v_add_f32_e32 v23, 1.0, v23
	v_add_f32_e32 v26, 1.0, v26
	v_add_f32_e32 v27, 1.0, v27
	v_rcp_f32_e32 v22, v22
	v_rcp_f32_e32 v23, v23
	v_rcp_f32_e32 v26, v26
	v_rcp_f32_e32 v27, v27
	v_pk_mul_f32 v[14:15], v[22:23], v[172:173]
	v_pk_mul_f32 v[12:13], v[22:23], v[176:177]
	s_nop 0
	v_exp_f32_e32 v22, v12
	v_exp_f32_e32 v23, v13
	v_fmaak_f32 v16, v14, v205, 0x3d2aaaab
	v_fmaak_f32 v19, v15, v205, 0x3d2aaaab
	v_fmaak_f32 v16, v16, v14, 0x3e2aaaab
	v_fmaak_f32 v19, v19, v15, 0x3e2aaaab
	v_fma_f32 v16, v16, v14, 0.5
	v_fma_f32 v19, v19, v15, 0.5
	v_fma_f32 v16, v16, v14, 1.0
	v_fma_f32 v19, v19, v15, 1.0
	v_mul_f32_e64 v17, v16, -v14
	v_mul_f32_e64 v12, v19, -v15
	v_fma_f32 v16, -v22, v22, 1.0
	v_cmp_lt_f32_e32 vcc, s6, v14
	v_fma_f32 v13, -v23, v23, 1.0
	s_nop 0
	v_cndmask_b32_e32 v16, v16, v17, vcc
	v_cmp_lt_f32_e32 vcc, s6, v15
	v_sqrt_f32_e32 v16, v16
	s_nop 1
	v_cndmask_b32_e32 v17, v13, v12, vcc
	v_sqrt_f32_e32 v17, v17
	s_nop 0
	v_pk_mul_f32 v[26:27], v[26:27], v[16:17]
	s_nop 0
	v_pk_mul_f32 v[26:27], v[30:31], v[26:27]
	ds_write_b128 v204, v[20:23] offset:46592
	ds_write_b128 v204, v[24:27] offset:62976
	s_waitcnt lgkmcnt(0)
	s_barrier
	ds_read2st64_b32 v[12:13], v132 offset0:134 offset1:198
	ds_read2st64_b32 v[14:15], v131 offset0:134 offset1:198
	ds_read2st64_b32 v[16:17], v130 offset0:134 offset1:198
	ds_read2st64_b32 v[62:63], v120 offset0:134 offset1:198
	ds_read2st64_b32 v[164:165], v119 offset0:134 offset1:198
	s_waitcnt lgkmcnt(4)
	v_fmac_f32_e32 v13, 0, v12
	s_waitcnt lgkmcnt(3)
	v_mul_f32_e32 v18, v12, v14
	s_waitcnt lgkmcnt(2)
	v_mul_f32_e32 v20, v18, v16
	ds_read2st64_b32 v[18:19], v129 offset0:134 offset1:198
	v_fmac_f32_e32 v15, v14, v13
	v_fmac_f32_e32 v17, v16, v15
	ds_read2st64_b32 v[166:167], v118 offset0:134 offset1:198
	ds_read2st64_b32 v[168:169], v59 offset0:134 offset1:198
	s_waitcnt lgkmcnt(2)
	v_mul_f32_e32 v22, v20, v18
	ds_read2st64_b32 v[20:21], v128 offset0:134 offset1:198
	v_fmac_f32_e32 v19, v18, v17
	s_waitcnt lgkmcnt(0)
	v_mul_f32_e32 v24, v22, v20
	ds_read2st64_b32 v[22:23], v127 offset0:134 offset1:198
	v_fmac_f32_e32 v21, v20, v19
	s_waitcnt lgkmcnt(0)
	v_mul_f32_e32 v26, v24, v22
	ds_read2st64_b32 v[24:25], v126 offset0:134 offset1:198
	v_fmac_f32_e32 v23, v22, v21
	s_waitcnt lgkmcnt(0)
	v_mul_f32_e32 v28, v26, v24
	ds_read2st64_b32 v[26:27], v125 offset0:134 offset1:198
	v_fmac_f32_e32 v25, v24, v23
	s_waitcnt lgkmcnt(0)
	v_mul_f32_e32 v30, v28, v26
	ds_read2st64_b32 v[28:29], v124 offset0:134 offset1:198
	v_fmac_f32_e32 v27, v26, v25
	s_waitcnt lgkmcnt(0)
	v_mul_f32_e32 v32, v30, v28
	ds_read2st64_b32 v[30:31], v123 offset0:134 offset1:198
	v_fmac_f32_e32 v29, v28, v27
	s_waitcnt lgkmcnt(0)
	v_mul_f32_e32 v34, v32, v30
	ds_read2st64_b32 v[32:33], v122 offset0:134 offset1:198
	v_fmac_f32_e32 v31, v30, v29
	s_waitcnt lgkmcnt(0)
	v_mul_f32_e32 v61, v34, v32
	ds_read2st64_b32 v[34:35], v121 offset0:134 offset1:198
	v_fmac_f32_e32 v33, v32, v31
	s_waitcnt lgkmcnt(0)
	v_mul_f32_e32 v61, v61, v34
	v_mul_f32_e32 v61, v61, v62
	v_fmac_f32_e32 v35, v34, v33
	v_mul_f32_e32 v61, v61, v164
	v_fmac_f32_e32 v63, v62, v35
	v_mul_f32_e32 v61, v61, v166
	v_fmac_f32_e32 v165, v164, v63
	v_mul_f32_e32 v61, v61, v168
	v_fmac_f32_e32 v167, v166, v165
	v_fmac_f32_e32 v169, v168, v167
	ds_write_b32 v98, v61
	ds_write_b32 v100, v169 offset:1024
	s_waitcnt lgkmcnt(0)
	s_barrier
	s_and_saveexec_b64 s[56:57], s[48:49]
	s_cbranch_execnz .LBB0_221
	s_or_b64 exec, exec, s[56:57]
	s_and_saveexec_b64 s[56:57], s[50:51]
	s_cbranch_execnz .LBB0_222

; __device__ __forceinline__ int TIDX() { int t = threadIdx.x; asm volatile("" : "+v"(t)); return t; }
; __device__ __forceinline__ int BIDX() { int b = blockIdx.x; asm volatile("" : "+s"(b)); return b; }
; template <bool FINAL>
; __device__ void phase_lru(const Params& p, int l, unsigned char* smem) {
;     ...
;   const int tid = TIDX(), lane = tid & 63, w = tid >> 6, l15 = lane & 15, g = lane >> 4;
;   const int e_ = tid & 63, qd = tid >> 6;
;   const int NIT = NCHUNK * 8;
;   const int step = gridDim.x;
;   int it = BIDX();
;   uint4 x0 = make_uint4(0, 0, 0, 0), x1 = x0, x2 = x0;
;   auto load_x = [&](int item, uint4& a0, uint4& a1, uint4& a2) {
;     const int ci = item >> 3, nb = item & 7;
;     const int tb = ci * 64, pos0 = tok_pos(tb), S = tok_len(tb);
;     const u16* zb = p.Z + (long)(tb - 2) * DIN + C_LX + nb * 64;
;     { int idx = tid, r = idx >> 3, ch = idx & 7, pp = pos0 - 2 + r;
;       a0 = (pp >= 0 && pp < S) ? *(const uint4*)(zb + (long)r * DIN + ch * 8) : make_uint4(0, 0, 0, 0); }
;     { int idx = tid + 256, r = idx >> 3, ch = idx & 7, pp = pos0 - 2 + r;
;       a1 = (pp >= 0 && pp < S) ? *(const uint4*)(zb + (long)r * DIN + ch * 8) : make_uint4(0, 0, 0, 0); }
;     { int idx = tid + 512, r = idx >> 3, ch = idx & 7, pp = pos0 - 2 + r;
;       a2 = (idx < 67 * 8 && pp >= 0 && pp < S) ? *(const uint4*)(zb + (long)r * DIN + ch * 8) : make_uint4(0, 0, 0, 0); }
;   };
;   if (it < NIT) load_x(it, x0, x1, x2);
;   for (; it < NIT; it += step) {
;     const int ci = it >> 3, nb = it & 7;
;     const int tb = ci * 64;
;     __syncthreads();
;     *(uint4*)(xs + (tid >> 3) * 64 + (tid & 7) * 8) = x0;
;     *(uint4*)(xs + ((tid + 256) >> 3) * 64 + (tid & 7) * 8) = x1;
;     if (tid + 512 < 67 * 8) *(uint4*)(xs + ((tid + 512) >> 3) * 64 + (tid & 7) * 8) = x2;
.LBB0_373:
	s_or_b64 exec, exec, s[40:41]
	v_and_b32_e32 v59, 63, v45
	v_and_b32_e32 v12, 0x7fffffc0, v12
	v_ashrrev_i32_e32 v13, 6, v45
	v_lshlrev_b32_e32 v16, 1, v59
	v_lshlrev_b32_e32 v12, 1, v12
	v_lshlrev_b32_e32 v18, 1, v144
	v_and_b32_e32 v60, 15, v45
	v_add_u32_e32 v17, 0, v16
	v_add3_u32 v61, 0, v12, v18
	v_lshlrev_b32_e32 v18, 4, v13
	v_add_u32_e32 v62, v17, v16
	v_or_b32_e32 v16, v18, v60
	v_mul_lo_u32 v19, v16, s28
	v_and_b32_e32 v20, 48, v45
	v_bfe_u32 v14, v45, 4, 2
	v_add3_u32 v46, 0, v19, v20
	v_and_b32_e32 v19, 0x3fffffc0, v45
	s_lshl_b32 s36, s72, 6
	s_and_b32 s30, 0xffff, s42
	v_lshlrev_b32_e32 v44, 3, v14
	v_lshlrev_b32_e32 v63, 2, v14
	v_lshlrev_b32_e32 v14, 2, v45
	v_readlane_b32 s4, v248, 16
	v_lshlrev_b32_e32 v19, 2, v19
	v_lshlrev_b32_e32 v20, 2, v59
	s_cmp_lg_u32 s30, 0
	v_add_u32_e32 v64, s4, v14
	v_add3_u32 v65, s4, v19, v20
	s_movk_i32 s4, 0x70
	s_cselect_b64 s[42:43], -1, 0
	v_mad_u64_u32 v[48:49], s[46:47], v16, s4, v[46:47]
	v_readlane_b32 s4, v248, 17
	s_cmp_lg_u64 s[42:43], 0
	v_mad_i64_i32 v[40:41], s[30:31], v47, s26, 0
	v_mad_i64_i32 v[42:43], s[30:31], v57, s26, 0
	v_add_u32_e32 v97, s4, v14
	v_readlane_b32 s4, v248, 18
	s_addc_u32 s62, s58, 0
	s_lshl_b32 s30, s22, 1
	v_add_u32_e32 v98, s4, v14
	v_readlane_b32 s4, v248, 19
	s_or_b32 s50, s30, 1
	s_ashr_i32 s31, s30, 31
	v_add_u32_e32 v99, s4, v14
	v_readlane_b32 s4, v248, 20
	s_lshl_b32 s44, s22, 10
	s_lshl_b32 s52, s50, 9
	v_add_u32_e32 v100, s4, v14
	v_readlane_b32 s4, v250, 5
	s_lshl_b32 s63, s22, 11
	s_lshl_b32 s64, s22, 9
	s_ashr_i32 s45, s44, 31
	s_ashr_i32 s51, s50, 31
	s_ashr_i32 s53, s52, 31
	s_lshl_b64 s[30:31], s[30:31], 17
	v_readlane_b32 s10, v250, 11
	v_or_b32_e32 v18, 1, v18
	v_readlane_b32 s11, v250, 12
	v_readlane_b32 s16, v250, 17
	v_readlane_b32 s17, v250, 18
	v_readlane_b32 s18, v250, 19
	v_readlane_b32 s19, v250, 20
	s_add_u32 s94, s10, s30
	v_lshlrev_b32_e32 v12, 11, v13
	v_lshlrev_b32_e32 v66, 12, v13
	v_mul_lo_u32 v13, v13, s27
	v_lshlrev_b32_e32 v67, 8, v18
	v_mul_lo_u32 v18, v18, s28
	s_mov_b32 s98, s22
	s_addc_u32 s95, s11, s31
	v_readlane_b32 s16, v250, 37
	s_lshl_b64 s[48:49], s[44:45], 2
	v_readlane_b32 s24, v250, 45
	v_readlane_b32 s25, v250, 46
	s_add_u32 s44, s24, s48
	v_readlane_b32 s28, v250, 49
	s_addc_u32 s45, s25, s49
	v_or_b32_e32 v16, v66, v20
	v_readlane_b32 s29, v250, 50
	s_add_u32 s46, s28, s48
	v_or_b32_e32 v68, 0x200, v66
	v_add_u32_e32 v49, 0, v16
	v_or_b32_e32 v16, v67, v20
	v_readlane_b32 s14, v250, 15
	s_addc_u32 s47, s29, s49
	v_or_b32_e32 v69, 0x300, v66
	v_add_u32_e32 v82, 0, v16
	v_or_b32_e32 v16, v68, v20
	v_readlane_b32 s15, v250, 16
	s_add_u32 s48, s14, s48
	v_or_b32_e32 v70, 0x400, v66
	v_add_u32_e32 v83, 0, v16
	v_or_b32_e32 v16, v69, v20
	s_addc_u32 s49, s15, s49
	s_lshl_b64 s[50:51], s[50:51], 17
	v_or_b32_e32 v71, 0x500, v66
	v_add_u32_e32 v84, 0, v16
	v_or_b32_e32 v16, v70, v20
	s_add_u32 s50, s10, s50
	v_or_b32_e32 v72, 0x600, v66
	v_add_u32_e32 v85, 0, v16
	v_or_b32_e32 v16, v71, v20
	s_addc_u32 s51, s11, s51
	s_lshl_b64 s[56:57], s[52:53], 2
	v_or_b32_e32 v73, 0x700, v66
	v_add_u32_e32 v86, 0, v16
	v_or_b32_e32 v16, v72, v20
	s_add_u32 s52, s24, s56
	v_or_b32_e32 v74, 0x800, v66
	v_add_u32_e32 v87, 0, v16
	v_or_b32_e32 v16, v73, v20
	s_addc_u32 s53, s25, s57
	v_or_b32_e32 v75, 0x900, v66
	v_add_u32_e32 v88, 0, v16
	v_or_b32_e32 v16, v74, v20
	s_add_u32 s54, s28, s56
	v_or_b32_e32 v76, 0xa00, v66
	v_add_u32_e32 v89, 0, v16
	v_or_b32_e32 v16, v75, v20
	s_addc_u32 s55, s29, s57
	v_or_b32_e32 v77, 0xb00, v66
	v_add_u32_e32 v90, 0, v16
	v_or_b32_e32 v16, v76, v20
	s_add_u32 s56, s14, s56
	v_or_b32_e32 v78, 0xc00, v66
	v_add_u32_e32 v91, 0, v16
	v_or_b32_e32 v16, v77, v20
	s_addc_u32 s57, s15, s57
	s_lshl_b32 s65, s62, 6
	v_or_b32_e32 v79, 0xd00, v66
	v_add_u32_e32 v92, 0, v16
	v_or_b32_e32 v16, v78, v20
	s_cmp_lg_u64 s[42:43], 0
	v_cndmask_b32_e64 v15, 0, 1, s[42:43]
	v_or_b32_e32 v80, 0xe00, v66
	v_add_u32_e32 v93, 0, v16
	v_or_b32_e32 v16, v79, v20
	s_addc_u32 s42, s72, s58
	v_or_b32_e32 v81, 0xf00, v66
	v_add_u32_e32 v94, 0, v16
	v_or_b32_e32 v16, v80, v20
	s_lshl_b32 s66, s42, 3
	v_readfirstlane_b32 s42, v15
	v_add_u32_e32 v95, 0, v16
	v_or_b32_e32 v16, v81, v20
; template <bool FINAL>
; __device__ void phase_lru(const Params& p, int l, unsigned char* smem) {
;     ...
;         uf[0] = *(const bf16x8*)(ub + (16 * w + l15) * 72 + g * 8);
;         uf[1] = *(const bf16x8*)(ub + (16 * w + l15) * 72 + 32 + g * 8);
;         const int t = 16 * w + l15;
; #pragma unroll
;         for (int et = 0; et < 4; ++et) {
;           f32x4 ar = {0.f, 0.f, 0.f, 0.f}, ai = {0.f, 0.f, 0.f, 0.f};
;           const u16* wr = p.WLRU + ((((size_t)(l * 2 + d) * 2 + 0) * 8 + nb) * 64 + et * 16 + l15) * 64 + g * 8;
;           const u16* wi = p.WLRU + ((((size_t)(l * 2 + d) * 2 + 1) * 8 + nb) * 64 + et * 16 + l15) * 64 + g * 8;
; #pragma unroll
;           for (int ks = 0; ks < 2; ++ks) {
;             ar = mfma16(*(const bf16x8*)(wr + ks * 32), uf[ks], ar);
;             ai = mfma16(*(const bf16x8*)(wi + ks * 32), uf[ks], ai);
;           }
;           const int e0 = et * 16 + 4 * g, ch0 = nb * 64 + e0;
;           const float4 ba4 = *(const float4*)(p.ba + (l * 2 + d) * 512 + ch0);
;           const float4 bx4 = *(const float4*)(p.bx + (l * 2 + d) * 512 + ch0);
;           const float4 sp4 = *(const float4*)(p.SP8 + (l * 2 + d) * 512 + ch0);
	s_lshl_b32 s68, s58, 6
	s_lshl_b32 s42, s42, 6
	v_cmp_gt_u32_e64 s[40:41], 64, v45
	v_add_u32_e32 v96, 0, v16
	s_lshl_b32 s67, s62, 3
	s_add_i32 s68, s68, s42
	v_add_u32_e32 v101, v17, v12
	v_add_u32_e32 v102, v17, v13
	v_add_u32_e32 v103, v17, v18
	v_readlane_b32 s5, v250, 6
	v_readlane_b32 s6, v250, 7
	v_readlane_b32 s7, v250, 8
	v_readlane_b32 s8, v250, 9
	v_readlane_b32 s9, v250, 10
	v_readlane_b32 s12, v250, 13
	v_readlane_b32 s13, v250, 14
	v_readlane_b32 s17, v250, 38
	v_readlane_b32 s18, v250, 39
	v_readlane_b32 s19, v250, 40
	v_readlane_b32 s20, v250, 41
	v_readlane_b32 s21, v250, 42
	v_readlane_b32 s22, v250, 43
	v_readlane_b32 s23, v250, 44
	v_readlane_b32 s26, v250, 47
	v_readlane_b32 s27, v250, 48
	v_readlane_b32 s30, v250, 51
	v_readlane_b32 s31, v250, 52
	s_and_b32 s32, s36, 0x1c0
	v_lshrrev_b32_e32 v12, 6, v147
	v_and_b32_e32 v22, 15, v147
	v_lshlrev_b32_e32 v13, 4, v12
	v_or_b32_e32 v13, v13, v22
	v_or_b32_e32 v13, s32, v13
	v_lshlrev_b32_e32 v14, 7, v13
	v_mov_b32_e32 v15, v145
	v_bfe_u32 v16, v147, 4, 2
	v_lshlrev_b32_e32 v17, 4, v16
	v_add_u32_e32 v14, v14, v17
	v_lshl_add_u64 v[18:19], s[94:95], 0, v[14:15]
	global_load_dwordx4 v[180:183], v[18:19], off
	global_load_dwordx4 v[184:187], v[18:19], off offset:64
	v_add_co_u32_e32 v20, vcc, 0x10000, v18
	s_nop 0
	v_addc_co_u32_e32 v21, vcc, 0, v19, vcc
	global_load_dwordx4 v[188:191], v[20:21], off
	global_load_dwordx4 v[192:195], v[20:21], off offset:64
	v_lshl_add_u64 v[18:19], s[50:51], 0, v[14:15]
	global_load_dwordx4 v[232:235], v[18:19], off
	global_load_dwordx4 v[236:239], v[18:19], off offset:64
	v_add_co_u32_e32 v20, vcc, 0x10000, v18
	s_nop 0
	v_addc_co_u32_e32 v21, vcc, 0, v19, vcc
	global_load_dwordx4 v[240:243], v[20:21], off
	global_load_dwordx4 v[244:247], v[20:21], off offset:64
	v_mul_u32_u24_e32 v229, 0x90, v22
	v_add_u32_e32 v229, v229, v17
	v_lshlrev_b32_e32 v230, 8, v22
	v_add_u32_e32 v230, v230, v17
	v_lshl_add_u32 v230, v12, 6, v230
	v_lshlrev_b32_e32 v231, 4, v12
	v_lshl_add_u32 v231, v16, 2, v231
	v_or_b32_e32 v231, s32, v231
	v_lshlrev_b32_e32 v231, 2, v231
	v_mov_b32_e32 v205, 0x3c088889
	v_lshl_add_u32 v204, v12, 2, v16
	v_xor_b32_e32 v204, v204, v22
	v_lshlrev_b32_e32 v204, 4, v204
	v_lshl_add_u32 v204, v22, 8, v204
	v_xor_b32_e32 v82, 0x10, v82
	v_xor_b32_e32 v83, 0x20, v83
	v_xor_b32_e32 v84, 0x30, v84
	v_xor_b32_e32 v85, 0x40, v85
	v_xor_b32_e32 v86, 0x50, v86
	v_xor_b32_e32 v87, 0x60, v87
	v_xor_b32_e32 v88, 0x70, v88
	v_xor_b32_e32 v89, 0x80, v89
	v_xor_b32_e32 v90, 0x90, v90
	v_xor_b32_e32 v91, 0xa0, v91
	v_xor_b32_e32 v92, 0xb0, v92
	v_xor_b32_e32 v93, 0xc0, v93
	v_xor_b32_e32 v94, 0xd0, v94
	v_xor_b32_e32 v95, 0xe0, v95
	v_xor_b32_e32 v96, 0xf0, v96
	global_load_dwordx4 v[122:125], v231, s[44:45]
	global_load_dwordx4 v[126:129], v231, s[46:47]
	global_load_dwordx4 v[130:133], v231, s[48:49]
	global_load_dwordx4 v[134:137], v231, s[52:53]
	global_load_dwordx4 v[138:141], v231, s[54:55]
	global_load_dwordx4 v[150:153], v231, s[56:57]
	s_waitcnt vmcnt(0)
	v_mul_f32_e32 v122, 0xbfb8aa3b, v122
	v_mul_f32_e32 v123, 0xbfb8aa3b, v123
	v_mul_f32_e32 v124, 0xbfb8aa3b, v124
	v_mul_f32_e32 v125, 0xbfb8aa3b, v125
	v_mul_f32_e32 v126, 0xbfb8aa3b, v126
	v_mul_f32_e32 v127, 0xbfb8aa3b, v127
	v_mul_f32_e32 v128, 0xbfb8aa3b, v128
	v_mul_f32_e32 v129, 0xbfb8aa3b, v129
	v_mul_f32_e32 v134, 0xbfb8aa3b, v134
	v_mul_f32_e32 v135, 0xbfb8aa3b, v135
	v_mul_f32_e32 v136, 0xbfb8aa3b, v136
	v_mul_f32_e32 v137, 0xbfb8aa3b, v137
	v_mul_f32_e32 v138, 0xbfb8aa3b, v138
	v_mul_f32_e32 v139, 0xbfb8aa3b, v139
	v_mul_f32_e32 v140, 0xbfb8aa3b, v140
	v_mul_f32_e32 v141, 0xbfb8aa3b, v141
	v_add_f32_e32 v154, v130, v130
	v_add_f32_e32 v155, v131, v131
	v_add_f32_e32 v156, v132, v132
	v_add_f32_e32 v157, v133, v133
	v_mul_f32_e32 v158, 0x3fb8aa3b, v130
	v_mul_f32_e32 v159, 0x3fb8aa3b, v131
	v_mul_f32_e32 v160, 0x3fb8aa3b, v132
	v_mul_f32_e32 v161, 0x3fb8aa3b, v133
	v_add_f32_e32 v162, v150, v150
	v_add_f32_e32 v163, v151, v151
	v_add_f32_e32 v164, v152, v152
	v_add_f32_e32 v165, v153, v153
	v_mul_f32_e32 v166, 0x3fb8aa3b, v150
	v_mul_f32_e32 v167, 0x3fb8aa3b, v151
	v_mul_f32_e32 v168, 0x3fb8aa3b, v152
	v_mul_f32_e32 v169, 0x3fb8aa3b, v153
	s_branch .LBB0_375

; __device__ __forceinline__ float bf2f(unsigned h) { return __uint_as_float(h << 16); }
; template <bool FINAL>
; __device__ void phase_lru(const Params& p, int l, unsigned char* smem) {
;     ...
;     if (it + step < NIT) load_x(it + step, x0, x1, x2);
;     {
;       const int ch = nb * 64 + e_;
;       const float cw0 = p.conv_w[(l * 4 + 0) * 512 + ch], cw1 = p.conv_w[(l * 4 + 1) * 512 + ch],
;                   cw2 = p.conv_w[(l * 4 + 2) * 512 + ch], cw3 = p.conv_w[(l * 4 + 3) * 512 + ch];
;       const float cb = p.conv_b[l * 512 + ch];
;       float xv[19];
; #pragma unroll
;       for (int k = 0; k < 19; ++k) xv[k] = bf2f(xs[(qd * 16 + k) * 64 + e_]);
; #pragma unroll
;       for (int tt = 0; tt < 16; ++tt) {
;         const int t = qd * 16 + tt;
;         const float u = cb + xv[tt] * cw0 + xv[tt + 1] * cw1 + xv[tt + 2] * cw2 + xv[tt + 3] * cw3;
;         u32[t * 64 + e_] = u;
;         ub[t * 72 + e_] = (u16)f2bf(u);
;       }
;     }
.LBB0_385:
	s_and_b32 s60, s36, 0x1c0
	v_or_b32_e32 v18, s60, v59
	v_or_b32_e32 v12, s63, v18
	v_readlane_b32 s4, v250, 37
	v_ashrrev_i32_e32 v13, 31, v12
	v_readlane_b32 s6, v250, 39
	v_readlane_b32 s7, v250, 40
	v_readlane_b32 s8, v250, 41
	v_readlane_b32 s9, v250, 42
	v_lshl_add_u64 v[14:15], v[12:13], 2, s[6:7]
	v_add_co_u32_e32 v16, vcc, 0x1000, v14
	global_load_dword v13, v[14:15], off
	global_load_dword v12, v[14:15], off offset:2048
	v_addc_co_u32_e32 v17, vcc, 0, v15, vcc
	global_load_dword v15, v[16:17], off
	global_load_dword v14, v[16:17], off offset:2048
	v_or_b32_e32 v16, s64, v18
	v_ashrrev_i32_e32 v17, 31, v16
	v_lshl_add_u64 v[16:17], v[16:17], 2, s[8:9]
	global_load_dword v16, v[16:17], off
	ds_read_u16 v17, v101
	ds_read_u16 v18, v101 offset:128
	ds_read_u16 v19, v101 offset:256
	ds_read_u16 v20, v101 offset:384
	ds_read_u16 v21, v101 offset:512
	ds_read_u16 v22, v101 offset:640
	ds_read_u16 v23, v101 offset:768
	ds_read_u16 v24, v101 offset:896
	s_waitcnt lgkmcnt(7)
	v_lshlrev_b32_e32 v17, 16, v17
	s_waitcnt lgkmcnt(6)
	v_lshlrev_b32_e32 v18, 16, v18
	s_waitcnt lgkmcnt(5)
	v_lshlrev_b32_e32 v19, 16, v19
	s_waitcnt lgkmcnt(4)
	v_lshlrev_b32_e32 v20, 16, v20
	v_add_u32_e32 v50, v62, v66
	ds_read_u16 v25, v101 offset:1024
	ds_read_u16 v26, v101 offset:1152
	ds_read_u16 v27, v101 offset:1280
	ds_read_u16 v28, v101 offset:1408
	ds_read_u16 v29, v101 offset:1536
	ds_read_u16 v30, v101 offset:1664
	ds_read_u16 v31, v101 offset:1792
	ds_read_u16 v32, v101 offset:1920
	ds_read_u16 v33, v101 offset:2048
	ds_read_u16 v34, v101 offset:2176
	ds_read_u16 v35, v101 offset:2304
	s_waitcnt lgkmcnt(14)
	v_lshlrev_b32_e32 v21, 16, v21
	s_waitcnt lgkmcnt(13)
	v_lshlrev_b32_e32 v22, 16, v22
	s_waitcnt lgkmcnt(12)
	v_lshlrev_b32_e32 v23, 16, v23
	s_waitcnt lgkmcnt(11)
	v_lshlrev_b32_e32 v24, 16, v24
	s_waitcnt lgkmcnt(10)
	v_lshlrev_b32_e32 v25, 16, v25
	s_waitcnt lgkmcnt(9)
	v_lshlrev_b32_e32 v26, 16, v26
	s_waitcnt lgkmcnt(8)
	v_lshlrev_b32_e32 v27, 16, v27
	s_waitcnt lgkmcnt(7)
	v_lshlrev_b32_e32 v28, 16, v28
	s_waitcnt lgkmcnt(6)
	v_lshlrev_b32_e32 v29, 16, v29
	s_waitcnt lgkmcnt(5)
	v_lshlrev_b32_e32 v30, 16, v30
	s_waitcnt lgkmcnt(4)
	v_lshlrev_b32_e32 v31, 16, v31
	s_waitcnt lgkmcnt(3)
	v_lshlrev_b32_e32 v32, 16, v32
	s_waitcnt lgkmcnt(2)
	v_lshlrev_b32_e32 v33, 16, v33
	s_ashr_i32 s42, s72, 3
	s_ashr_i32 s43, s42, 31
	s_waitcnt lgkmcnt(1)
	v_lshlrev_b32_e32 v34, 16, v34
	s_lshl_b64 s[42:43], s[42:43], 10
	v_add_u32_e32 v144, s60, v45
	s_waitcnt lgkmcnt(0)
	v_lshlrev_b32_e32 v35, 16, v35
	v_lshlrev_b32_e32 v54, 1, v44
	v_mov_b32_e32 v55, v145
	v_readlane_b32 s5, v250, 38
	s_mov_b64 s[4:5], 0x10000
	v_or_b32_e32 v56, s60, v63
	v_lshlrev_b32_e32 v104, 2, v56
	s_mov_b32 s6, 0xbe800000
	s_mov_b64 s[8:9], 0x10800
	v_readlane_b32 s10, v250, 43
	v_readlane_b32 s11, v250, 44
	v_readlane_b32 s12, v250, 45
	v_readlane_b32 s13, v250, 46
	v_readlane_b32 s14, v250, 47
	v_readlane_b32 s15, v250, 48
	v_readlane_b32 s16, v250, 49
	v_readlane_b32 s17, v250, 50
	v_readlane_b32 s18, v250, 51
	v_readlane_b32 s19, v250, 52
	s_waitcnt vmcnt(0)
	v_fma_f32 v17, v13, v17, v16
	v_fmac_f32_e32 v17, v12, v18
	v_fmac_f32_e32 v17, v15, v19
	v_fmac_f32_e32 v17, v14, v20
	ds_write_b32 v50, v17 offset:8704
	v_cvt_pk_bf16_f32 v17, v17, s0
	ds_write_b16 v102, v17 offset:25088
	v_fma_f32 v17, v13, v18, v16
	v_fmac_f32_e32 v17, v12, v19
	v_fmac_f32_e32 v17, v15, v20
	v_fmac_f32_e32 v17, v14, v21
	v_add_u32_e32 v18, v62, v67
	ds_write_b32 v18, v17 offset:8704
	v_cvt_pk_bf16_f32 v17, v17, s0
	ds_write_b16 v103, v17 offset:25088
	v_fma_f32 v17, v13, v19, v16
	v_fmac_f32_e32 v17, v12, v20
	v_fmac_f32_e32 v17, v15, v21
	v_fmac_f32_e32 v17, v14, v22
	v_add_u32_e32 v18, v62, v68
	ds_write_b32 v18, v17 offset:8704
	v_cvt_pk_bf16_f32 v17, v17, s0
	ds_write_b16 v103, v17 offset:25232
	v_fma_f32 v17, v13, v20, v16
	v_fmac_f32_e32 v17, v12, v21
	v_fmac_f32_e32 v17, v15, v22
	v_fmac_f32_e32 v17, v14, v23
	v_add_u32_e32 v18, v62, v69
	ds_write_b32 v18, v17 offset:8704
	v_cvt_pk_bf16_f32 v17, v17, s0
	ds_write_b16 v103, v17 offset:25376
	v_fma_f32 v17, v13, v21, v16
	v_fmac_f32_e32 v17, v12, v22
	v_fmac_f32_e32 v17, v15, v23
	v_fmac_f32_e32 v17, v14, v24
	v_add_u32_e32 v18, v62, v70
	ds_write_b32 v18, v17 offset:8704
	v_cvt_pk_bf16_f32 v17, v17, s0
	ds_write_b16 v103, v17 offset:25520
	v_fma_f32 v17, v13, v22, v16
	v_fmac_f32_e32 v17, v12, v23
	v_fmac_f32_e32 v17, v15, v24
	v_fmac_f32_e32 v17, v14, v25
	v_add_u32_e32 v18, v62, v71
	ds_write_b32 v18, v17 offset:8704
	v_cvt_pk_bf16_f32 v17, v17, s0
	ds_write_b16 v103, v17 offset:25664
	v_fma_f32 v17, v13, v23, v16
	v_fmac_f32_e32 v17, v12, v24
	v_fmac_f32_e32 v17, v15, v25
	v_fmac_f32_e32 v17, v14, v26
	v_add_u32_e32 v18, v62, v72
	ds_write_b32 v18, v17 offset:8704
	v_cvt_pk_bf16_f32 v17, v17, s0
	ds_write_b16 v103, v17 offset:25808
	v_fma_f32 v17, v13, v24, v16
	v_fmac_f32_e32 v17, v12, v25
	v_fmac_f32_e32 v17, v15, v26
	v_fmac_f32_e32 v17, v14, v27
	v_add_u32_e32 v18, v62, v73
	ds_write_b32 v18, v17 offset:8704
	v_cvt_pk_bf16_f32 v17, v17, s0
	ds_write_b16 v103, v17 offset:25952
	v_fma_f32 v17, v13, v25, v16
	v_fmac_f32_e32 v17, v12, v26
	v_fmac_f32_e32 v17, v15, v27
	v_fmac_f32_e32 v17, v14, v28
	v_add_u32_e32 v18, v62, v74
	ds_write_b32 v18, v17 offset:8704
	v_cvt_pk_bf16_f32 v17, v17, s0
	ds_write_b16 v103, v17 offset:26096
	v_fma_f32 v17, v13, v26, v16
	v_fmac_f32_e32 v17, v12, v27
	v_fmac_f32_e32 v17, v15, v28
	v_fmac_f32_e32 v17, v14, v29
	v_add_u32_e32 v18, v62, v75
	ds_write_b32 v18, v17 offset:8704
	v_cvt_pk_bf16_f32 v17, v17, s0
	ds_write_b16 v103, v17 offset:26240
	v_fma_f32 v17, v13, v27, v16
	v_fmac_f32_e32 v17, v12, v28
; template <bool FINAL>
; __device__ void phase_lru(const Params& p, int l, unsigned char* smem) {
;     ...
;       for (int tt = 0; tt < 16; ++tt) {
;         const int t = qd * 16 + tt;
;         const float u = cb + xv[tt] * cw0 + xv[tt + 1] * cw1 + xv[tt + 2] * cw2 + xv[tt + 3] * cw3;
;         u32[t * 64 + e_] = u;
;         ub[t * 72 + e_] = (u16)f2bf(u);
;       }
;     }
;     __syncthreads();
;     if (FINAL) {
;       *(uint4*)(xs + (tid >> 3) * 64 + (tid & 7) * 8) = gz0;
;       *(uint4*)(xs + ((tid >> 3) + 32) * 64 + (tid & 7) * 8) = gz1;
;     }
;     float hsum[16];
; #pragma unroll
;     for (int tt = 0; tt < 16; ++tt) hsum[tt] = 0.f;
; #pragma unroll
;     for (int d = 0; d < 2; ++d) {
;       {
;         bf16x8 uf[2];
;         uf[0] = *(const bf16x8*)(ub + (16 * w + l15) * 72 + g * 8);
;         uf[1] = *(const bf16x8*)(ub + (16 * w + l15) * 72 + 32 + g * 8);
;         const int t = 16 * w + l15;
; #pragma unroll
;         for (int et = 0; et < 4; ++et) {
;           f32x4 ar = {0.f, 0.f, 0.f, 0.f}, ai = {0.f, 0.f, 0.f, 0.f};
;           const u16* wr = p.WLRU + ((((size_t)(l * 2 + d) * 2 + 0) * 8 + nb) * 64 + et * 16 + l15) * 64 + g * 8;
;           const u16* wi = p.WLRU + ((((size_t)(l * 2 + d) * 2 + 1) * 8 + nb) * 64 + et * 16 + l15) * 64 + g * 8;
; #pragma unroll
;           for (int ks = 0; ks < 2; ++ks) {
;             ar = mfma16(*(const bf16x8*)(wr + ks * 32), uf[ks], ar);
;             ai = mfma16(*(const bf16x8*)(wi + ks * 32), uf[ks], ai);
;           }
;           const int e0 = et * 16 + 4 * g, ch0 = nb * 64 + e0;
;           const float4 ba4 = *(const float4*)(p.ba + (l * 2 + d) * 512 + ch0);
;           const float4 bx4 = *(const float4*)(p.bx + (l * 2 + d) * 512 + ch0);
;           const float4 sp4 = *(const float4*)(p.SP8 + (l * 2 + d) * 512 + ch0);
;           const float4 uu = *(const float4*)(u32 + t * 64 + e0);
;           const float* bap = (const float*)&ba4; const float* bxp = (const float*)&bx4;
;           const float* spp = (const float*)&sp4; const float* uup = (const float*)&uu;
;           f32x4 av, bv;
; #pragma unroll
;           for (int j = 0; j < 4; ++j) {
;             float r = sigmoidf_(ar[j] + bap[j]);
;             float ig = sigmoidf_(ai[j] + bxp[j]);
;             float la = spp[j] * r;
;             float av_ = __expf(la);
;             float t2 = 2.0f * la;
	v_fmac_f32_e32 v17, v15, v29
	v_fmac_f32_e32 v17, v14, v30
	v_add_u32_e32 v18, v62, v76
	ds_write_b32 v18, v17 offset:8704
	v_cvt_pk_bf16_f32 v17, v17, s0
	ds_write_b16 v103, v17 offset:26384
	v_fma_f32 v17, v13, v28, v16
	v_fmac_f32_e32 v17, v12, v29
	v_fmac_f32_e32 v17, v15, v30
	v_fmac_f32_e32 v17, v14, v31
	v_add_u32_e32 v18, v62, v77
	ds_write_b32 v18, v17 offset:8704
	v_cvt_pk_bf16_f32 v17, v17, s0
	ds_write_b16 v103, v17 offset:26528
	v_fma_f32 v17, v13, v29, v16
	v_fmac_f32_e32 v17, v12, v30
	v_fmac_f32_e32 v17, v15, v31
	v_fmac_f32_e32 v17, v14, v32
	v_add_u32_e32 v18, v62, v78
	ds_write_b32 v18, v17 offset:8704
	v_cvt_pk_bf16_f32 v17, v17, s0
	ds_write_b16 v103, v17 offset:26672
	v_fma_f32 v17, v13, v30, v16
	v_fmac_f32_e32 v17, v12, v31
	v_fmac_f32_e32 v17, v15, v32
	v_fmac_f32_e32 v17, v14, v33
	v_add_u32_e32 v18, v62, v79
	ds_write_b32 v18, v17 offset:8704
	v_cvt_pk_bf16_f32 v17, v17, s0
	ds_write_b16 v103, v17 offset:26816
	v_fma_f32 v17, v13, v31, v16
	v_fmac_f32_e32 v16, v13, v32
	v_fmac_f32_e32 v17, v12, v32
	v_fmac_f32_e32 v16, v12, v33
	v_or_b32_e32 v20, s60, v60
	v_fmac_f32_e32 v17, v15, v33
	v_fmac_f32_e32 v16, v15, v34
	v_lshl_add_u64 v[50:51], v[144:145], 0, s[42:43]
	v_lshlrev_b32_e32 v144, 7, v20
	v_fmac_f32_e32 v17, v14, v34
	v_add_u32_e32 v18, v62, v80
	v_fmac_f32_e32 v16, v14, v35
	v_add_u32_e32 v12, v62, v81
	v_lshl_add_u64 v[20:21], s[94:95], 0, v[144:145]
	ds_write_b32 v18, v17 offset:8704
	v_cvt_pk_bf16_f32 v17, v17, s0
	ds_write_b32 v12, v16 offset:8704
	v_cvt_pk_bf16_f32 v12, v16, s0
	v_lshl_add_u64 v[28:29], v[20:21], 0, v[54:55]
	ds_write_b16 v103, v17 offset:26960
	ds_write_b16 v103, v12 offset:27104
	s_waitcnt lgkmcnt(0)
	s_barrier
	s_mov_b32 s5, 0x3e4ccccd
	ds_read_b128 v[12:15], v229 offset:25088
	ds_read_b128 v[16:19], v229 offset:25152
	ds_read_b128 v[28:31], v230 offset:8704
	s_waitcnt lgkmcnt(1)
	v_mfma_f32_16x16x32_bf16 v[20:23], v[180:183], v[12:15], 0
	v_mfma_f32_16x16x32_bf16 v[24:27], v[188:191], v[12:15], 0
	v_mfma_f32_16x16x32_bf16 v[20:23], v[184:187], v[16:19], v[20:23]
	v_mfma_f32_16x16x32_bf16 v[24:27], v[192:195], v[16:19], v[24:27]
	s_nop 7
	s_nop 3
	s_waitcnt lgkmcnt(0)
	v_fmamk_f32 v20, v20, 0xbfb8aa3b, v122
	v_fmamk_f32 v21, v21, 0xbfb8aa3b, v123
	v_fmamk_f32 v24, v24, 0xbfb8aa3b, v126
	v_fmamk_f32 v25, v25, 0xbfb8aa3b, v127
	v_exp_f32_e32 v20, v20
	v_exp_f32_e32 v21, v21
	v_exp_f32_e32 v24, v24
	v_exp_f32_e32 v25, v25
	v_add_f32_e32 v20, 1.0, v20
	v_add_f32_e32 v21, 1.0, v21
	v_add_f32_e32 v24, 1.0, v24
	v_add_f32_e32 v25, 1.0, v25
	v_rcp_f32_e32 v20, v20
	v_rcp_f32_e32 v21, v21
	v_rcp_f32_e32 v24, v24
	v_rcp_f32_e32 v25, v25
	v_pk_mul_f32 v[14:15], v[20:21], v[154:155]
	v_pk_mul_f32 v[12:13], v[20:21], v[158:159]
	s_nop 0
	v_exp_f32_e32 v20, v12
	v_exp_f32_e32 v21, v13
	v_fmaak_f32 v16, v14, v205, 0x3d2aaaab
	v_fmaak_f32 v19, v15, v205, 0x3d2aaaab
	v_fmaak_f32 v16, v16, v14, 0x3e2aaaab
	v_fmaak_f32 v19, v19, v15, 0x3e2aaaab
	v_fma_f32 v16, v16, v14, 0.5
	v_fma_f32 v19, v19, v15, 0.5
	v_fma_f32 v16, v16, v14, 1.0
	v_fma_f32 v19, v19, v15, 1.0
	v_mul_f32_e64 v17, v16, -v14
	v_mul_f32_e64 v12, v19, -v15
	v_fma_f32 v16, -v20, v20, 1.0
	v_cmp_lt_f32_e32 vcc, s6, v14
	v_fma_f32 v13, -v21, v21, 1.0
	s_nop 0
	v_cndmask_b32_e32 v16, v16, v17, vcc
	v_cmp_lt_f32_e32 vcc, s6, v15
	v_sqrt_f32_e32 v16, v16
	s_nop 1
	v_cndmask_b32_e32 v17, v13, v12, vcc
	v_sqrt_f32_e32 v17, v17
	s_nop 0
	v_pk_mul_f32 v[24:25], v[24:25], v[16:17]
	s_nop 0
	v_pk_mul_f32 v[24:25], v[28:29], v[24:25]
	v_fmamk_f32 v22, v22, 0xbfb8aa3b, v124
	v_fmamk_f32 v23, v23, 0xbfb8aa3b, v125
	v_fmamk_f32 v26, v26, 0xbfb8aa3b, v128
	v_fmamk_f32 v27, v27, 0xbfb8aa3b, v129
	v_exp_f32_e32 v22, v22
	v_exp_f32_e32 v23, v23
	v_exp_f32_e32 v26, v26
	v_exp_f32_e32 v27, v27
	v_add_f32_e32 v22, 1.0, v22
	v_add_f32_e32 v23, 1.0, v23
	v_add_f32_e32 v26, 1.0, v26
	v_add_f32_e32 v27, 1.0, v27
	v_rcp_f32_e32 v22, v22
	v_rcp_f32_e32 v23, v23
	v_rcp_f32_e32 v26, v26
	v_rcp_f32_e32 v27, v27
	v_pk_mul_f32 v[14:15], v[22:23], v[156:157]
	v_pk_mul_f32 v[12:13], v[22:23], v[160:161]
	s_nop 0
	v_exp_f32_e32 v22, v12
	v_exp_f32_e32 v23, v13
	v_fmaak_f32 v16, v14, v205, 0x3d2aaaab
	v_fmaak_f32 v19, v15, v205, 0x3d2aaaab
	v_fmaak_f32 v16, v16, v14, 0x3e2aaaab
	v_fmaak_f32 v19, v19, v15, 0x3e2aaaab
	v_fma_f32 v16, v16, v14, 0.5
	v_fma_f32 v19, v19, v15, 0.5
	v_fma_f32 v16, v16, v14, 1.0
	v_fma_f32 v19, v19, v15, 1.0
	v_mul_f32_e64 v17, v16, -v14
	v_mul_f32_e64 v12, v19, -v15
	v_fma_f32 v16, -v22, v22, 1.0
	v_cmp_lt_f32_e32 vcc, s6, v14
	v_fma_f32 v13, -v23, v23, 1.0
	s_nop 0
	v_cndmask_b32_e32 v16, v16, v17, vcc
	v_cmp_lt_f32_e32 vcc, s6, v15
	v_sqrt_f32_e32 v16, v16
	s_nop 1
	v_cndmask_b32_e32 v17, v13, v12, vcc
	v_sqrt_f32_e32 v17, v17
	s_nop 0
	v_pk_mul_f32 v[26:27], v[26:27], v[16:17]
	s_nop 0
	v_pk_mul_f32 v[26:27], v[30:31], v[26:27]
	ds_write_b128 v204, v[20:23] offset:34304
	ds_write_b128 v204, v[24:27] offset:50688
	ds_read_b128 v[12:15], v229 offset:27392
	ds_read_b128 v[16:19], v229 offset:27456
	ds_read_b128 v[28:31], v230 offset:12800
	s_waitcnt lgkmcnt(1)
	v_mfma_f32_16x16x32_bf16 v[20:23], v[180:183], v[12:15], 0
	v_mfma_f32_16x16x32_bf16 v[24:27], v[188:191], v[12:15], 0
	v_mfma_f32_16x16x32_bf16 v[20:23], v[184:187], v[16:19], v[20:23]
	v_mfma_f32_16x16x32_bf16 v[24:27], v[192:195], v[16:19], v[24:27]
	s_nop 7
	s_nop 3
	s_waitcnt lgkmcnt(0)
; __device__ __forceinline__ float sigmoidf_(float x) { return __builtin_amdgcn_rcpf(1.0f + __expf(-x)); }
; template <bool FINAL>
; __device__ void phase_lru(const Params& p, int l, unsigned char* smem) {
;     ...
;           const int e0 = et * 16 + 4 * g, ch0 = nb * 64 + e0;
;           const float4 ba4 = *(const float4*)(p.ba + (l * 2 + d) * 512 + ch0);
;           const float4 bx4 = *(const float4*)(p.bx + (l * 2 + d) * 512 + ch0);
;           const float4 sp4 = *(const float4*)(p.SP8 + (l * 2 + d) * 512 + ch0);
;           const float4 uu = *(const float4*)(u32 + t * 64 + e0);
;           const float* bap = (const float*)&ba4; const float* bxp = (const float*)&bx4;
;           const float* spp = (const float*)&sp4; const float* uup = (const float*)&uu;
;           f32x4 av, bv;
; #pragma unroll
;           for (int j = 0; j < 4; ++j) {
;             float r = sigmoidf_(ar[j] + bap[j]);
;             float ig = sigmoidf_(ai[j] + bxp[j]);
;             float la = spp[j] * r;
;             float av_ = __expf(la);
;             float t2 = 2.0f * la;
;             float ser = -t2 * (1.f + t2 * 0.5f * (1.f + t2 * (1.f / 3.f) * (1.f + t2 * 0.25f * (1.f + t2 * 0.2f))));
;             float om = (t2 > -0.25f) ? ser : (1.0f - av_ * av_);
;             av[j] = av_;
;             bv[j] = __builtin_amdgcn_sqrtf(om) * ig * uup[j];
;           }
;           *(f32x4*)(sa + t * 64 + e0) = av;
;           *(f32x4*)(sb + t * 64 + e0) = bv;
;         }
	v_fmamk_f32 v20, v20, 0xbfb8aa3b, v122
	v_fmamk_f32 v21, v21, 0xbfb8aa3b, v123
	v_fmamk_f32 v24, v24, 0xbfb8aa3b, v126
	v_fmamk_f32 v25, v25, 0xbfb8aa3b, v127
	v_exp_f32_e32 v20, v20
	v_exp_f32_e32 v21, v21
	v_exp_f32_e32 v24, v24
	v_exp_f32_e32 v25, v25
	v_add_f32_e32 v20, 1.0, v20
	v_add_f32_e32 v21, 1.0, v21
	v_add_f32_e32 v24, 1.0, v24
	v_add_f32_e32 v25, 1.0, v25
	v_rcp_f32_e32 v20, v20
	v_rcp_f32_e32 v21, v21
	v_rcp_f32_e32 v24, v24
	v_rcp_f32_e32 v25, v25
	v_pk_mul_f32 v[14:15], v[20:21], v[154:155]
	v_pk_mul_f32 v[12:13], v[20:21], v[158:159]
	s_nop 0
	v_exp_f32_e32 v20, v12
	v_exp_f32_e32 v21, v13
	v_fmaak_f32 v16, v14, v205, 0x3d2aaaab
	v_fmaak_f32 v19, v15, v205, 0x3d2aaaab
	v_fmaak_f32 v16, v16, v14, 0x3e2aaaab
	v_fmaak_f32 v19, v19, v15, 0x3e2aaaab
	v_fma_f32 v16, v16, v14, 0.5
	v_fma_f32 v19, v19, v15, 0.5
	v_fma_f32 v16, v16, v14, 1.0
	v_fma_f32 v19, v19, v15, 1.0
	v_mul_f32_e64 v17, v16, -v14
	v_mul_f32_e64 v12, v19, -v15
	v_fma_f32 v16, -v20, v20, 1.0
	v_cmp_lt_f32_e32 vcc, s6, v14
	v_fma_f32 v13, -v21, v21, 1.0
	s_nop 0
	v_cndmask_b32_e32 v16, v16, v17, vcc
	v_cmp_lt_f32_e32 vcc, s6, v15
	v_sqrt_f32_e32 v16, v16
	s_nop 1
	v_cndmask_b32_e32 v17, v13, v12, vcc
	v_sqrt_f32_e32 v17, v17
	s_nop 0
	v_pk_mul_f32 v[24:25], v[24:25], v[16:17]
	s_nop 0
	v_pk_mul_f32 v[24:25], v[28:29], v[24:25]
	v_fmamk_f32 v22, v22, 0xbfb8aa3b, v124
	v_fmamk_f32 v23, v23, 0xbfb8aa3b, v125
	v_fmamk_f32 v26, v26, 0xbfb8aa3b, v128
	v_fmamk_f32 v27, v27, 0xbfb8aa3b, v129
	v_exp_f32_e32 v22, v22
	v_exp_f32_e32 v23, v23
	v_exp_f32_e32 v26, v26
	v_exp_f32_e32 v27, v27
	v_add_f32_e32 v22, 1.0, v22
	v_add_f32_e32 v23, 1.0, v23
	v_add_f32_e32 v26, 1.0, v26
	v_add_f32_e32 v27, 1.0, v27
	v_rcp_f32_e32 v22, v22
	v_rcp_f32_e32 v23, v23
	v_rcp_f32_e32 v26, v26
	v_rcp_f32_e32 v27, v27
	v_pk_mul_f32 v[14:15], v[22:23], v[156:157]
	v_pk_mul_f32 v[12:13], v[22:23], v[160:161]
	s_nop 0
	v_exp_f32_e32 v22, v12
	v_exp_f32_e32 v23, v13
	v_fmaak_f32 v16, v14, v205, 0x3d2aaaab
	v_fmaak_f32 v19, v15, v205, 0x3d2aaaab
	v_fmaak_f32 v16, v16, v14, 0x3e2aaaab
	v_fmaak_f32 v19, v19, v15, 0x3e2aaaab
	v_fma_f32 v16, v16, v14, 0.5
	v_fma_f32 v19, v19, v15, 0.5
	v_fma_f32 v16, v16, v14, 1.0
	v_fma_f32 v19, v19, v15, 1.0
	v_mul_f32_e64 v17, v16, -v14
	v_mul_f32_e64 v12, v19, -v15
	v_fma_f32 v16, -v22, v22, 1.0
	v_cmp_lt_f32_e32 vcc, s6, v14
	v_fma_f32 v13, -v23, v23, 1.0
	s_nop 0
	v_cndmask_b32_e32 v16, v16, v17, vcc
	v_cmp_lt_f32_e32 vcc, s6, v15
	v_sqrt_f32_e32 v16, v16
	s_nop 1
	v_cndmask_b32_e32 v17, v13, v12, vcc
	v_sqrt_f32_e32 v17, v17
	s_nop 0
	v_pk_mul_f32 v[26:27], v[26:27], v[16:17]
	s_nop 0
	v_pk_mul_f32 v[26:27], v[30:31], v[26:27]
	ds_write_b128 v204, v[20:23] offset:38400
	ds_write_b128 v204, v[24:27] offset:54784
	ds_read_b128 v[12:15], v229 offset:29696
	ds_read_b128 v[16:19], v229 offset:29760
	ds_read_b128 v[28:31], v230 offset:16896
	s_waitcnt lgkmcnt(1)
	v_mfma_f32_16x16x32_bf16 v[20:23], v[180:183], v[12:15], 0
	v_mfma_f32_16x16x32_bf16 v[24:27], v[188:191], v[12:15], 0
	v_mfma_f32_16x16x32_bf16 v[20:23], v[184:187], v[16:19], v[20:23]
	v_mfma_f32_16x16x32_bf16 v[24:27], v[192:195], v[16:19], v[24:27]
	s_nop 7
	s_nop 3
	s_waitcnt lgkmcnt(0)
	v_fmamk_f32 v20, v20, 0xbfb8aa3b, v122
	v_fmamk_f32 v21, v21, 0xbfb8aa3b, v123
	v_fmamk_f32 v24, v24, 0xbfb8aa3b, v126
	v_fmamk_f32 v25, v25, 0xbfb8aa3b, v127
	v_exp_f32_e32 v20, v20
	v_exp_f32_e32 v21, v21
	v_exp_f32_e32 v24, v24
	v_exp_f32_e32 v25, v25
	v_add_f32_e32 v20, 1.0, v20
	v_add_f32_e32 v21, 1.0, v21
	v_add_f32_e32 v24, 1.0, v24
	v_add_f32_e32 v25, 1.0, v25
	v_rcp_f32_e32 v20, v20
	v_rcp_f32_e32 v21, v21
	v_rcp_f32_e32 v24, v24
	v_rcp_f32_e32 v25, v25
	v_pk_mul_f32 v[14:15], v[20:21], v[154:155]
	v_pk_mul_f32 v[12:13], v[20:21], v[158:159]
	s_nop 0
	v_exp_f32_e32 v20, v12
	v_exp_f32_e32 v21, v13
	v_fmaak_f32 v16, v14, v205, 0x3d2aaaab
	v_fmaak_f32 v19, v15, v205, 0x3d2aaaab
	v_fmaak_f32 v16, v16, v14, 0x3e2aaaab
	v_fmaak_f32 v19, v19, v15, 0x3e2aaaab
	v_fma_f32 v16, v16, v14, 0.5
	v_fma_f32 v19, v19, v15, 0.5
	v_fma_f32 v16, v16, v14, 1.0
	v_fma_f32 v19, v19, v15, 1.0
	v_mul_f32_e64 v17, v16, -v14
	v_mul_f32_e64 v12, v19, -v15
	v_fma_f32 v16, -v20, v20, 1.0
	v_cmp_lt_f32_e32 vcc, s6, v14
	v_fma_f32 v13, -v21, v21, 1.0
	s_nop 0
	v_cndmask_b32_e32 v16, v16, v17, vcc
	v_cmp_lt_f32_e32 vcc, s6, v15
	v_sqrt_f32_e32 v16, v16
	s_nop 1
	v_cndmask_b32_e32 v17, v13, v12, vcc
	v_sqrt_f32_e32 v17, v17
	s_nop 0
	v_pk_mul_f32 v[24:25], v[24:25], v[16:17]
	s_nop 0
	v_pk_mul_f32 v[24:25], v[28:29], v[24:25]
	v_fmamk_f32 v22, v22, 0xbfb8aa3b, v124
	v_fmamk_f32 v23, v23, 0xbfb8aa3b, v125
	v_fmamk_f32 v26, v26, 0xbfb8aa3b, v128
	v_fmamk_f32 v27, v27, 0xbfb8aa3b, v129
	v_exp_f32_e32 v22, v22
	v_exp_f32_e32 v23, v23
	v_exp_f32_e32 v26, v26
	v_exp_f32_e32 v27, v27
	v_add_f32_e32 v22, 1.0, v22
	v_add_f32_e32 v23, 1.0, v23
	v_add_f32_e32 v26, 1.0, v26
	v_add_f32_e32 v27, 1.0, v27
	v_rcp_f32_e32 v22, v22
	v_rcp_f32_e32 v23, v23
	v_rcp_f32_e32 v26, v26
	v_rcp_f32_e32 v27, v27
	v_pk_mul_f32 v[14:15], v[22:23], v[156:157]
	v_pk_mul_f32 v[12:13], v[22:23], v[160:161]
	s_nop 0
	v_exp_f32_e32 v22, v12
	v_exp_f32_e32 v23, v13
	v_fmaak_f32 v16, v14, v205, 0x3d2aaaab
	v_fmaak_f32 v19, v15, v205, 0x3d2aaaab
	v_fmaak_f32 v16, v16, v14, 0x3e2aaaab
	v_fmaak_f32 v19, v19, v15, 0x3e2aaaab
	v_fma_f32 v16, v16, v14, 0.5
	v_fma_f32 v19, v19, v15, 0.5
	v_fma_f32 v16, v16, v14, 1.0
	v_fma_f32 v19, v19, v15, 1.0
	v_mul_f32_e64 v17, v16, -v14
	v_mul_f32_e64 v12, v19, -v15
	v_fma_f32 v16, -v22, v22, 1.0
	v_cmp_lt_f32_e32 vcc, s6, v14
	v_fma_f32 v13, -v23, v23, 1.0
	s_nop 0
	v_cndmask_b32_e32 v16, v16, v17, vcc
	v_cmp_lt_f32_e32 vcc, s6, v15
	v_sqrt_f32_e32 v16, v16
	s_nop 1
	v_cndmask_b32_e32 v17, v13, v12, vcc
	v_sqrt_f32_e32 v17, v17
	s_nop 0
	v_pk_mul_f32 v[26:27], v[26:27], v[16:17]
	s_nop 0
	v_pk_mul_f32 v[26:27], v[30:31], v[26:27]
	ds_write_b128 v204, v[20:23] offset:42496
	ds_write_b128 v204, v[24:27] offset:58880
	ds_read_b128 v[12:15], v229 offset:32000
	ds_read_b128 v[16:19], v229 offset:32064
	ds_read_b128 v[28:31], v230 offset:20992
	s_waitcnt lgkmcnt(1)
; template <bool FINAL>
; __device__ void phase_lru(const Params& p, int l, unsigned char* smem) {
;     ...
;           const int e0 = et * 16 + 4 * g, ch0 = nb * 64 + e0;
;           const float4 ba4 = *(const float4*)(p.ba + (l * 2 + d) * 512 + ch0);
;           const float4 bx4 = *(const float4*)(p.bx + (l * 2 + d) * 512 + ch0);
;           const float4 sp4 = *(const float4*)(p.SP8 + (l * 2 + d) * 512 + ch0);
;           const float4 uu = *(const float4*)(u32 + t * 64 + e0);
;           const float* bap = (const float*)&ba4; const float* bxp = (const float*)&bx4;
;           const float* spp = (const float*)&sp4; const float* uup = (const float*)&uu;
;           f32x4 av, bv;
; #pragma unroll
;           for (int j = 0; j < 4; ++j) {
;             float r = sigmoidf_(ar[j] + bap[j]);
;             float ig = sigmoidf_(ai[j] + bxp[j]);
;             float la = spp[j] * r;
;             float av_ = __expf(la);
;             float t2 = 2.0f * la;
;             float ser = -t2 * (1.f + t2 * 0.5f * (1.f + t2 * (1.f / 3.f) * (1.f + t2 * 0.25f * (1.f + t2 * 0.2f))));
;             float om = (t2 > -0.25f) ? ser : (1.0f - av_ * av_);
;             av[j] = av_;
;             bv[j] = __builtin_amdgcn_sqrtf(om) * ig * uup[j];
;           }
;           *(f32x4*)(sa + t * 64 + e0) = av;
;           *(f32x4*)(sb + t * 64 + e0) = bv;
;         }
;       }
;       __syncthreads();
;       {
;         float A = 1.f, B = 0.f;
;         if (d == 0) {
; #pragma unroll
;           for (int tt = 0; tt < 16; ++tt) { int t = qd * 16 + tt; float a = sa[t * 64 + e_], b = sb[t * 64 + e_]; B = a * B + b; A *= a; }
;         } else {
; #pragma unroll
;     ...
;         }
;         part[(0 * 4 + qd) * 64 + e_] = A;
;         part[(1 * 4 + qd) * 64 + e_] = B;
;       }
;       __syncthreads();
;       if (!FINAL) {
;         if (qd == 0) {
;           float A = 1.f, B = 0.f;
;           if (d == 0) {
; #pragma unroll
;             for (int q = 0; q < 4; ++q) { float aq = part[q * 64 + e_], bq = part[(4 + q) * 64 + e_]; B = aq * B + bq; A *= aq; }
;           } else {
; #pragma unroll
;             for (int q = 3; q >= 0; --q) { float aq = part[q * 64 + e_], bq = part[(4 + q) * 64 + e_]; B = aq * B + bq; A *= aq; }
;           }
;           const size_t cidx = ((size_t)ci * 2 + d) * 512 + nb * 64 + e_;
;           p.CA[cidx] = A; p.CB[cidx] = B;
;         }
	v_mfma_f32_16x16x32_bf16 v[20:23], v[180:183], v[12:15], 0
	v_mfma_f32_16x16x32_bf16 v[24:27], v[188:191], v[12:15], 0
	v_mfma_f32_16x16x32_bf16 v[20:23], v[184:187], v[16:19], v[20:23]
	v_mfma_f32_16x16x32_bf16 v[24:27], v[192:195], v[16:19], v[24:27]
	s_nop 7
	s_nop 3
	s_waitcnt lgkmcnt(0)
	v_fmamk_f32 v20, v20, 0xbfb8aa3b, v122
	v_fmamk_f32 v21, v21, 0xbfb8aa3b, v123
	v_fmamk_f32 v24, v24, 0xbfb8aa3b, v126
	v_fmamk_f32 v25, v25, 0xbfb8aa3b, v127
	v_exp_f32_e32 v20, v20
	v_exp_f32_e32 v21, v21
	v_exp_f32_e32 v24, v24
	v_exp_f32_e32 v25, v25
	v_add_f32_e32 v20, 1.0, v20
	v_add_f32_e32 v21, 1.0, v21
	v_add_f32_e32 v24, 1.0, v24
	v_add_f32_e32 v25, 1.0, v25
	v_rcp_f32_e32 v20, v20
	v_rcp_f32_e32 v21, v21
	v_rcp_f32_e32 v24, v24
	v_rcp_f32_e32 v25, v25
	v_pk_mul_f32 v[14:15], v[20:21], v[154:155]
	v_pk_mul_f32 v[12:13], v[20:21], v[158:159]
	s_nop 0
	v_exp_f32_e32 v20, v12
	v_exp_f32_e32 v21, v13
	v_fmaak_f32 v16, v14, v205, 0x3d2aaaab
	v_fmaak_f32 v19, v15, v205, 0x3d2aaaab
	v_fmaak_f32 v16, v16, v14, 0x3e2aaaab
	v_fmaak_f32 v19, v19, v15, 0x3e2aaaab
	v_fma_f32 v16, v16, v14, 0.5
	v_fma_f32 v19, v19, v15, 0.5
	v_fma_f32 v16, v16, v14, 1.0
	v_fma_f32 v19, v19, v15, 1.0
	v_mul_f32_e64 v17, v16, -v14
	v_mul_f32_e64 v12, v19, -v15
	v_fma_f32 v16, -v20, v20, 1.0
	v_cmp_lt_f32_e32 vcc, s6, v14
	v_fma_f32 v13, -v21, v21, 1.0
	s_nop 0
	v_cndmask_b32_e32 v16, v16, v17, vcc
	v_cmp_lt_f32_e32 vcc, s6, v15
	v_sqrt_f32_e32 v16, v16
	s_nop 1
	v_cndmask_b32_e32 v17, v13, v12, vcc
	v_sqrt_f32_e32 v17, v17
	s_nop 0
	v_pk_mul_f32 v[24:25], v[24:25], v[16:17]
	s_nop 0
	v_pk_mul_f32 v[24:25], v[28:29], v[24:25]
	v_fmamk_f32 v22, v22, 0xbfb8aa3b, v124
	v_fmamk_f32 v23, v23, 0xbfb8aa3b, v125
	v_fmamk_f32 v26, v26, 0xbfb8aa3b, v128
	v_fmamk_f32 v27, v27, 0xbfb8aa3b, v129
	v_exp_f32_e32 v22, v22
	v_exp_f32_e32 v23, v23
	v_exp_f32_e32 v26, v26
	v_exp_f32_e32 v27, v27
	v_add_f32_e32 v22, 1.0, v22
	v_add_f32_e32 v23, 1.0, v23
	v_add_f32_e32 v26, 1.0, v26
	v_add_f32_e32 v27, 1.0, v27
	v_rcp_f32_e32 v22, v22
	v_rcp_f32_e32 v23, v23
	v_rcp_f32_e32 v26, v26
	v_rcp_f32_e32 v27, v27
	v_pk_mul_f32 v[14:15], v[22:23], v[156:157]
	v_pk_mul_f32 v[12:13], v[22:23], v[160:161]
	s_nop 0
	v_exp_f32_e32 v22, v12
	v_exp_f32_e32 v23, v13
	v_fmaak_f32 v16, v14, v205, 0x3d2aaaab
	v_fmaak_f32 v19, v15, v205, 0x3d2aaaab
	v_fmaak_f32 v16, v16, v14, 0x3e2aaaab
	v_fmaak_f32 v19, v19, v15, 0x3e2aaaab
	v_fma_f32 v16, v16, v14, 0.5
	v_fma_f32 v19, v19, v15, 0.5
	v_fma_f32 v16, v16, v14, 1.0
	v_fma_f32 v19, v19, v15, 1.0
	v_mul_f32_e64 v17, v16, -v14
	v_mul_f32_e64 v12, v19, -v15
	v_fma_f32 v16, -v22, v22, 1.0
	v_cmp_lt_f32_e32 vcc, s6, v14
	v_fma_f32 v13, -v23, v23, 1.0
	s_nop 0
	v_cndmask_b32_e32 v16, v16, v17, vcc
	v_cmp_lt_f32_e32 vcc, s6, v15
	v_sqrt_f32_e32 v16, v16
	s_nop 1
	v_cndmask_b32_e32 v17, v13, v12, vcc
	v_sqrt_f32_e32 v17, v17
	s_nop 0
	v_pk_mul_f32 v[26:27], v[26:27], v[16:17]
	s_nop 0
	v_pk_mul_f32 v[26:27], v[30:31], v[26:27]
	ds_write_b128 v204, v[20:23] offset:46592
	ds_write_b128 v204, v[24:27] offset:62976
	s_waitcnt lgkmcnt(0)
	s_barrier
	ds_read2st64_b32 v[12:13], v49 offset0:134 offset1:198
	ds_read2st64_b32 v[14:15], v82 offset0:134 offset1:198
	ds_read2st64_b32 v[16:17], v83 offset0:134 offset1:198
	s_waitcnt lgkmcnt(2)
	v_fmac_f32_e32 v13, 0, v12
	s_waitcnt lgkmcnt(1)
	v_mul_f32_e32 v18, v12, v14
	s_waitcnt lgkmcnt(0)
	v_mul_f32_e32 v20, v18, v16
	ds_read2st64_b32 v[18:19], v84 offset0:134 offset1:198
	v_fmac_f32_e32 v15, v14, v13
	v_fmac_f32_e32 v17, v16, v15
	v_lshlrev_b64 v[12:13], 2, v[50:51]
	v_lshl_add_u64 v[50:51], s[86:87], 0, v[12:13]
	s_waitcnt lgkmcnt(0)
	v_mul_f32_e32 v22, v20, v18
	ds_read2st64_b32 v[20:21], v85 offset0:134 offset1:198
	v_fmac_f32_e32 v19, v18, v17
	s_waitcnt lgkmcnt(0)
	v_mul_f32_e32 v24, v22, v20
	ds_read2st64_b32 v[22:23], v86 offset0:134 offset1:198
	v_fmac_f32_e32 v21, v20, v19
	s_waitcnt lgkmcnt(0)
	v_mul_f32_e32 v26, v24, v22
	ds_read2st64_b32 v[24:25], v87 offset0:134 offset1:198
	v_fmac_f32_e32 v23, v22, v21
	s_waitcnt lgkmcnt(0)
	v_mul_f32_e32 v28, v26, v24
	ds_read2st64_b32 v[26:27], v88 offset0:134 offset1:198
	v_fmac_f32_e32 v25, v24, v23
	s_waitcnt lgkmcnt(0)
	v_mul_f32_e32 v30, v28, v26
	ds_read2st64_b32 v[28:29], v89 offset0:134 offset1:198
	v_fmac_f32_e32 v27, v26, v25
	s_waitcnt lgkmcnt(0)
	v_mul_f32_e32 v32, v30, v28
	ds_read2st64_b32 v[30:31], v90 offset0:134 offset1:198
	v_fmac_f32_e32 v29, v28, v27
	s_waitcnt lgkmcnt(0)
	v_mul_f32_e32 v34, v32, v30
	ds_read2st64_b32 v[32:33], v91 offset0:134 offset1:198
	v_fmac_f32_e32 v31, v30, v29
	s_waitcnt lgkmcnt(0)
	v_mul_f32_e32 v52, v34, v32
	ds_read2st64_b32 v[34:35], v92 offset0:134 offset1:198
	v_fmac_f32_e32 v33, v32, v31
	s_waitcnt lgkmcnt(0)
	v_mul_f32_e32 v104, v52, v34
	ds_read2st64_b32 v[52:53], v93 offset0:134 offset1:198
	v_fmac_f32_e32 v35, v34, v33
	s_waitcnt lgkmcnt(0)
	v_mul_f32_e32 v106, v104, v52
	ds_read2st64_b32 v[104:105], v94 offset0:134 offset1:198
	v_fmac_f32_e32 v53, v52, v35
	s_waitcnt lgkmcnt(0)
	v_mul_f32_e32 v108, v106, v104
	ds_read2st64_b32 v[106:107], v95 offset0:134 offset1:198
	v_fmac_f32_e32 v105, v104, v53
	v_lshl_add_u64 v[52:53], s[88:89], 0, v[12:13]
	s_waitcnt lgkmcnt(0)
	v_mul_f32_e32 v110, v108, v106
	ds_read2st64_b32 v[108:109], v96 offset0:134 offset1:198
	v_fmac_f32_e32 v107, v106, v105
	s_waitcnt lgkmcnt(0)
	v_mul_f32_e32 v110, v110, v108
	v_fmac_f32_e32 v109, v108, v107
	ds_write_b32 v64, v110
	ds_write_b32 v65, v109 offset:1024
	s_waitcnt lgkmcnt(0)
	s_barrier
	s_and_saveexec_b64 s[42:43], s[40:41]
	s_cbranch_execz .LBB0_387
	ds_read2st64_b32 v[12:13], v64 offset1:1
	ds_read2st64_b32 v[14:15], v64 offset0:2 offset1:3
	s_waitcnt lgkmcnt(1)
	v_mul_f32_e32 v16, v12, v13
	s_waitcnt lgkmcnt(0)
	v_mul_f32_e32 v16, v16, v14
	v_mul_f32_e32 v18, v16, v15
	ds_read2st64_b32 v[16:17], v64 offset0:4 offset1:5
	s_waitcnt lgkmcnt(0)
	v_fma_f32 v12, 0, v12, v16
	v_fmac_f32_e32 v17, v13, v12
	ds_read2st64_b32 v[12:13], v64 offset0:6 offset1:7
	s_waitcnt lgkmcnt(0)
	v_fma_f32 v12, v14, v17, v12
	v_fmac_f32_e32 v13, v15, v12
	global_store_dword v[50:51], v18, off
	global_store_dword v[52:53], v13, off
; __device__ __forceinline__ float sigmoidf_(float x) { return __builtin_amdgcn_rcpf(1.0f + __expf(-x)); }
; template <bool FINAL>
; __device__ void phase_lru(const Params& p, int l, unsigned char* smem) {
;     ...
;         uf[0] = *(const bf16x8*)(ub + (16 * w + l15) * 72 + g * 8);
;         uf[1] = *(const bf16x8*)(ub + (16 * w + l15) * 72 + 32 + g * 8);
;         const int t = 16 * w + l15;
; #pragma unroll
;         for (int et = 0; et < 4; ++et) {
;           f32x4 ar = {0.f, 0.f, 0.f, 0.f}, ai = {0.f, 0.f, 0.f, 0.f};
;           const u16* wr = p.WLRU + ((((size_t)(l * 2 + d) * 2 + 0) * 8 + nb) * 64 + et * 16 + l15) * 64 + g * 8;
;           const u16* wi = p.WLRU + ((((size_t)(l * 2 + d) * 2 + 1) * 8 + nb) * 64 + et * 16 + l15) * 64 + g * 8;
; #pragma unroll
;           for (int ks = 0; ks < 2; ++ks) {
;             ar = mfma16(*(const bf16x8*)(wr + ks * 32), uf[ks], ar);
;             ai = mfma16(*(const bf16x8*)(wi + ks * 32), uf[ks], ai);
;           }
;           const int e0 = et * 16 + 4 * g, ch0 = nb * 64 + e0;
;           const float4 ba4 = *(const float4*)(p.ba + (l * 2 + d) * 512 + ch0);
;           const float4 bx4 = *(const float4*)(p.bx + (l * 2 + d) * 512 + ch0);
;           const float4 sp4 = *(const float4*)(p.SP8 + (l * 2 + d) * 512 + ch0);
;           const float4 uu = *(const float4*)(u32 + t * 64 + e0);
;           const float* bap = (const float*)&ba4; const float* bxp = (const float*)&bx4;
;           const float* spp = (const float*)&sp4; const float* uup = (const float*)&uu;
;           f32x4 av, bv;
; #pragma unroll
;           for (int j = 0; j < 4; ++j) {
;             float r = sigmoidf_(ar[j] + bap[j]);
;             float ig = sigmoidf_(ai[j] + bxp[j]);
;             float la = spp[j] * r;
;             float av_ = __expf(la);
;             float t2 = 2.0f * la;
;             float ser = -t2 * (1.f + t2 * 0.5f * (1.f + t2 * (1.f / 3.f) * (1.f + t2 * 0.25f * (1.f + t2 * 0.2f))));
;             float om = (t2 > -0.25f) ? ser : (1.0f - av_ * av_);
;             av[j] = av_;
;             bv[j] = __builtin_amdgcn_sqrtf(om) * ig * uup[j];
;           }
;           *(f32x4*)(sa + t * 64 + e0) = av;
;           *(f32x4*)(sb + t * 64 + e0) = bv;
;         }
.LBB0_387:
	s_or_b64 exec, exec, s[42:43]
	v_lshl_add_u64 v[20:21], s[50:51], 0, v[144:145]
	v_lshl_add_u64 v[28:29], v[20:21], 0, v[54:55]
	s_barrier
	s_mov_b32 s5, 0x3e4ccccd
	ds_read_b128 v[12:15], v229 offset:25088
	ds_read_b128 v[16:19], v229 offset:25152
	ds_read_b128 v[28:31], v230 offset:8704
	s_waitcnt lgkmcnt(1)
	v_mfma_f32_16x16x32_bf16 v[20:23], v[232:235], v[12:15], 0
	v_mfma_f32_16x16x32_bf16 v[24:27], v[240:243], v[12:15], 0
	v_mfma_f32_16x16x32_bf16 v[20:23], v[236:239], v[16:19], v[20:23]
	v_mfma_f32_16x16x32_bf16 v[24:27], v[244:247], v[16:19], v[24:27]
	s_nop 7
	s_nop 3
	s_waitcnt lgkmcnt(0)
	v_fmamk_f32 v20, v20, 0xbfb8aa3b, v134
	v_fmamk_f32 v21, v21, 0xbfb8aa3b, v135
	v_fmamk_f32 v24, v24, 0xbfb8aa3b, v138
	v_fmamk_f32 v25, v25, 0xbfb8aa3b, v139
	v_exp_f32_e32 v20, v20
	v_exp_f32_e32 v21, v21
	v_exp_f32_e32 v24, v24
	v_exp_f32_e32 v25, v25
	v_add_f32_e32 v20, 1.0, v20
	v_add_f32_e32 v21, 1.0, v21
	v_add_f32_e32 v24, 1.0, v24
	v_add_f32_e32 v25, 1.0, v25
	v_rcp_f32_e32 v20, v20
	v_rcp_f32_e32 v21, v21
	v_rcp_f32_e32 v24, v24
	v_rcp_f32_e32 v25, v25
	v_pk_mul_f32 v[14:15], v[20:21], v[162:163]
	v_pk_mul_f32 v[12:13], v[20:21], v[166:167]
	s_nop 0
	v_exp_f32_e32 v20, v12
	v_exp_f32_e32 v21, v13
	v_fmaak_f32 v16, v14, v205, 0x3d2aaaab
	v_fmaak_f32 v19, v15, v205, 0x3d2aaaab
	v_fmaak_f32 v16, v16, v14, 0x3e2aaaab
	v_fmaak_f32 v19, v19, v15, 0x3e2aaaab
	v_fma_f32 v16, v16, v14, 0.5
	v_fma_f32 v19, v19, v15, 0.5
	v_fma_f32 v16, v16, v14, 1.0
	v_fma_f32 v19, v19, v15, 1.0
	v_mul_f32_e64 v17, v16, -v14
	v_mul_f32_e64 v12, v19, -v15
	v_fma_f32 v16, -v20, v20, 1.0
	v_cmp_lt_f32_e32 vcc, s6, v14
	v_fma_f32 v13, -v21, v21, 1.0
	s_nop 0
	v_cndmask_b32_e32 v16, v16, v17, vcc
	v_cmp_lt_f32_e32 vcc, s6, v15
	v_sqrt_f32_e32 v16, v16
	s_nop 1
	v_cndmask_b32_e32 v17, v13, v12, vcc
	v_sqrt_f32_e32 v17, v17
	s_nop 0
	v_pk_mul_f32 v[24:25], v[24:25], v[16:17]
	s_nop 0
	v_pk_mul_f32 v[24:25], v[28:29], v[24:25]
	v_fmamk_f32 v22, v22, 0xbfb8aa3b, v136
	v_fmamk_f32 v23, v23, 0xbfb8aa3b, v137
	v_fmamk_f32 v26, v26, 0xbfb8aa3b, v140
	v_fmamk_f32 v27, v27, 0xbfb8aa3b, v141
	v_exp_f32_e32 v22, v22
	v_exp_f32_e32 v23, v23
	v_exp_f32_e32 v26, v26
	v_exp_f32_e32 v27, v27
	v_add_f32_e32 v22, 1.0, v22
	v_add_f32_e32 v23, 1.0, v23
	v_add_f32_e32 v26, 1.0, v26
	v_add_f32_e32 v27, 1.0, v27
	v_rcp_f32_e32 v22, v22
	v_rcp_f32_e32 v23, v23
	v_rcp_f32_e32 v26, v26
	v_rcp_f32_e32 v27, v27
	v_pk_mul_f32 v[14:15], v[22:23], v[164:165]
	v_pk_mul_f32 v[12:13], v[22:23], v[168:169]
	s_nop 0
	v_exp_f32_e32 v22, v12
	v_exp_f32_e32 v23, v13
	v_fmaak_f32 v16, v14, v205, 0x3d2aaaab
	v_fmaak_f32 v19, v15, v205, 0x3d2aaaab
	v_fmaak_f32 v16, v16, v14, 0x3e2aaaab
	v_fmaak_f32 v19, v19, v15, 0x3e2aaaab
	v_fma_f32 v16, v16, v14, 0.5
	v_fma_f32 v19, v19, v15, 0.5
	v_fma_f32 v16, v16, v14, 1.0
	v_fma_f32 v19, v19, v15, 1.0
	v_mul_f32_e64 v17, v16, -v14
	v_mul_f32_e64 v12, v19, -v15
	v_fma_f32 v16, -v22, v22, 1.0
	v_cmp_lt_f32_e32 vcc, s6, v14
	v_fma_f32 v13, -v23, v23, 1.0
	s_nop 0
	v_cndmask_b32_e32 v16, v16, v17, vcc
	v_cmp_lt_f32_e32 vcc, s6, v15
	v_sqrt_f32_e32 v16, v16
	s_nop 1
	v_cndmask_b32_e32 v17, v13, v12, vcc
	v_sqrt_f32_e32 v17, v17
	s_nop 0
	v_pk_mul_f32 v[26:27], v[26:27], v[16:17]
	s_nop 0
	v_pk_mul_f32 v[26:27], v[30:31], v[26:27]
	ds_write_b128 v204, v[20:23] offset:34304
	ds_write_b128 v204, v[24:27] offset:50688
	ds_read_b128 v[12:15], v229 offset:27392
	ds_read_b128 v[16:19], v229 offset:27456
	ds_read_b128 v[28:31], v230 offset:12800
	s_waitcnt lgkmcnt(1)
	v_mfma_f32_16x16x32_bf16 v[20:23], v[232:235], v[12:15], 0
	v_mfma_f32_16x16x32_bf16 v[24:27], v[240:243], v[12:15], 0
	v_mfma_f32_16x16x32_bf16 v[20:23], v[236:239], v[16:19], v[20:23]
	v_mfma_f32_16x16x32_bf16 v[24:27], v[244:247], v[16:19], v[24:27]
	s_nop 7
	s_nop 3
	s_waitcnt lgkmcnt(0)
	v_fmamk_f32 v20, v20, 0xbfb8aa3b, v134
	v_fmamk_f32 v21, v21, 0xbfb8aa3b, v135
	v_fmamk_f32 v24, v24, 0xbfb8aa3b, v138
	v_fmamk_f32 v25, v25, 0xbfb8aa3b, v139
	v_exp_f32_e32 v20, v20
	v_exp_f32_e32 v21, v21
	v_exp_f32_e32 v24, v24
	v_exp_f32_e32 v25, v25
	v_add_f32_e32 v20, 1.0, v20
	v_add_f32_e32 v21, 1.0, v21
	v_add_f32_e32 v24, 1.0, v24
	v_add_f32_e32 v25, 1.0, v25
	v_rcp_f32_e32 v20, v20
	v_rcp_f32_e32 v21, v21
	v_rcp_f32_e32 v24, v24
	v_rcp_f32_e32 v25, v25
	v_pk_mul_f32 v[14:15], v[20:21], v[162:163]
	v_pk_mul_f32 v[12:13], v[20:21], v[166:167]
	s_nop 0
	v_exp_f32_e32 v20, v12
	v_exp_f32_e32 v21, v13
	v_fmaak_f32 v16, v14, v205, 0x3d2aaaab
	v_fmaak_f32 v19, v15, v205, 0x3d2aaaab
	v_fmaak_f32 v16, v16, v14, 0x3e2aaaab
	v_fmaak_f32 v19, v19, v15, 0x3e2aaaab
	v_fma_f32 v16, v16, v14, 0.5
	v_fma_f32 v19, v19, v15, 0.5
	v_fma_f32 v16, v16, v14, 1.0
	v_fma_f32 v19, v19, v15, 1.0
	v_mul_f32_e64 v17, v16, -v14
	v_mul_f32_e64 v12, v19, -v15
	v_fma_f32 v16, -v20, v20, 1.0
	v_cmp_lt_f32_e32 vcc, s6, v14
	v_fma_f32 v13, -v21, v21, 1.0
	s_nop 0
	v_cndmask_b32_e32 v16, v16, v17, vcc
	v_cmp_lt_f32_e32 vcc, s6, v15
	v_sqrt_f32_e32 v16, v16
	s_nop 1
	v_cndmask_b32_e32 v17, v13, v12, vcc
	v_sqrt_f32_e32 v17, v17
	s_nop 0
	v_pk_mul_f32 v[24:25], v[24:25], v[16:17]
	s_nop 0
	v_pk_mul_f32 v[24:25], v[28:29], v[24:25]
	v_fmamk_f32 v22, v22, 0xbfb8aa3b, v136
	v_fmamk_f32 v23, v23, 0xbfb8aa3b, v137
	v_fmamk_f32 v26, v26, 0xbfb8aa3b, v140
	v_fmamk_f32 v27, v27, 0xbfb8aa3b, v141
	v_exp_f32_e32 v22, v22
	v_exp_f32_e32 v23, v23
	v_exp_f32_e32 v26, v26
	v_exp_f32_e32 v27, v27
	v_add_f32_e32 v22, 1.0, v22
	v_add_f32_e32 v23, 1.0, v23
	v_add_f32_e32 v26, 1.0, v26
	v_add_f32_e32 v27, 1.0, v27
	v_rcp_f32_e32 v22, v22
	v_rcp_f32_e32 v23, v23
	v_rcp_f32_e32 v26, v26
	v_rcp_f32_e32 v27, v27
	v_pk_mul_f32 v[14:15], v[22:23], v[164:165]
	v_pk_mul_f32 v[12:13], v[22:23], v[168:169]
	s_nop 0
	v_exp_f32_e32 v22, v12
	v_exp_f32_e32 v23, v13
	v_fmaak_f32 v16, v14, v205, 0x3d2aaaab
	v_fmaak_f32 v19, v15, v205, 0x3d2aaaab
	v_fmaak_f32 v16, v16, v14, 0x3e2aaaab
	v_fmaak_f32 v19, v19, v15, 0x3e2aaaab
	v_fma_f32 v16, v16, v14, 0.5
	v_fma_f32 v19, v19, v15, 0.5
	v_fma_f32 v16, v16, v14, 1.0
	v_fma_f32 v19, v19, v15, 1.0
	v_mul_f32_e64 v17, v16, -v14
	v_mul_f32_e64 v12, v19, -v15
	v_fma_f32 v16, -v22, v22, 1.0
	v_cmp_lt_f32_e32 vcc, s6, v14
	v_fma_f32 v13, -v23, v23, 1.0
	s_nop 0
	v_cndmask_b32_e32 v16, v16, v17, vcc
	v_cmp_lt_f32_e32 vcc, s6, v15
	v_sqrt_f32_e32 v16, v16
	s_nop 1
	v_cndmask_b32_e32 v17, v13, v12, vcc
	v_sqrt_f32_e32 v17, v17
	s_nop 0
	v_pk_mul_f32 v[26:27], v[26:27], v[16:17]
	s_nop 0
	v_pk_mul_f32 v[26:27], v[30:31], v[26:27]
	ds_write_b128 v204, v[20:23] offset:38400
	ds_write_b128 v204, v[24:27] offset:54784
	ds_read_b128 v[12:15], v229 offset:29696
	ds_read_b128 v[16:19], v229 offset:29760
	ds_read_b128 v[28:31], v230 offset:16896
	s_waitcnt lgkmcnt(1)
; __device__ __forceinline__ float sigmoidf_(float x) { return __builtin_amdgcn_rcpf(1.0f + __expf(-x)); }
; template <bool FINAL>
; __device__ void phase_lru(const Params& p, int l, unsigned char* smem) {
;     ...
;         uf[0] = *(const bf16x8*)(ub + (16 * w + l15) * 72 + g * 8);
;         uf[1] = *(const bf16x8*)(ub + (16 * w + l15) * 72 + 32 + g * 8);
;         const int t = 16 * w + l15;
; #pragma unroll
;         for (int et = 0; et < 4; ++et) {
;           f32x4 ar = {0.f, 0.f, 0.f, 0.f}, ai = {0.f, 0.f, 0.f, 0.f};
;           const u16* wr = p.WLRU + ((((size_t)(l * 2 + d) * 2 + 0) * 8 + nb) * 64 + et * 16 + l15) * 64 + g * 8;
;           const u16* wi = p.WLRU + ((((size_t)(l * 2 + d) * 2 + 1) * 8 + nb) * 64 + et * 16 + l15) * 64 + g * 8;
; #pragma unroll
;           for (int ks = 0; ks < 2; ++ks) {
;             ar = mfma16(*(const bf16x8*)(wr + ks * 32), uf[ks], ar);
;             ai = mfma16(*(const bf16x8*)(wi + ks * 32), uf[ks], ai);
;           }
;           const int e0 = et * 16 + 4 * g, ch0 = nb * 64 + e0;
;           const float4 ba4 = *(const float4*)(p.ba + (l * 2 + d) * 512 + ch0);
;           const float4 bx4 = *(const float4*)(p.bx + (l * 2 + d) * 512 + ch0);
;           const float4 sp4 = *(const float4*)(p.SP8 + (l * 2 + d) * 512 + ch0);
;           const float4 uu = *(const float4*)(u32 + t * 64 + e0);
;           const float* bap = (const float*)&ba4; const float* bxp = (const float*)&bx4;
;           const float* spp = (const float*)&sp4; const float* uup = (const float*)&uu;
;           f32x4 av, bv;
; #pragma unroll
;           for (int j = 0; j < 4; ++j) {
;             float r = sigmoidf_(ar[j] + bap[j]);
;             float ig = sigmoidf_(ai[j] + bxp[j]);
;             float la = spp[j] * r;
;             float av_ = __expf(la);
;             float t2 = 2.0f * la;
;             float ser = -t2 * (1.f + t2 * 0.5f * (1.f + t2 * (1.f / 3.f) * (1.f + t2 * 0.25f * (1.f + t2 * 0.2f))));
;             float om = (t2 > -0.25f) ? ser : (1.0f - av_ * av_);
;             av[j] = av_;
;             bv[j] = __builtin_amdgcn_sqrtf(om) * ig * uup[j];
;           }
;           *(f32x4*)(sa + t * 64 + e0) = av;
;           *(f32x4*)(sb + t * 64 + e0) = bv;
;         }
	v_mfma_f32_16x16x32_bf16 v[20:23], v[232:235], v[12:15], 0
	v_mfma_f32_16x16x32_bf16 v[24:27], v[240:243], v[12:15], 0
	v_mfma_f32_16x16x32_bf16 v[20:23], v[236:239], v[16:19], v[20:23]
	v_mfma_f32_16x16x32_bf16 v[24:27], v[244:247], v[16:19], v[24:27]
	s_nop 7
	s_nop 3
	s_waitcnt lgkmcnt(0)
	v_fmamk_f32 v20, v20, 0xbfb8aa3b, v134
	v_fmamk_f32 v21, v21, 0xbfb8aa3b, v135
	v_fmamk_f32 v24, v24, 0xbfb8aa3b, v138
	v_fmamk_f32 v25, v25, 0xbfb8aa3b, v139
	v_exp_f32_e32 v20, v20
	v_exp_f32_e32 v21, v21
	v_exp_f32_e32 v24, v24
	v_exp_f32_e32 v25, v25
	v_add_f32_e32 v20, 1.0, v20
	v_add_f32_e32 v21, 1.0, v21
	v_add_f32_e32 v24, 1.0, v24
	v_add_f32_e32 v25, 1.0, v25
	v_rcp_f32_e32 v20, v20
	v_rcp_f32_e32 v21, v21
	v_rcp_f32_e32 v24, v24
	v_rcp_f32_e32 v25, v25
	v_pk_mul_f32 v[14:15], v[20:21], v[162:163]
	v_pk_mul_f32 v[12:13], v[20:21], v[166:167]
	s_nop 0
	v_exp_f32_e32 v20, v12
	v_exp_f32_e32 v21, v13
	v_fmaak_f32 v16, v14, v205, 0x3d2aaaab
	v_fmaak_f32 v19, v15, v205, 0x3d2aaaab
	v_fmaak_f32 v16, v16, v14, 0x3e2aaaab
	v_fmaak_f32 v19, v19, v15, 0x3e2aaaab
	v_fma_f32 v16, v16, v14, 0.5
	v_fma_f32 v19, v19, v15, 0.5
	v_fma_f32 v16, v16, v14, 1.0
	v_fma_f32 v19, v19, v15, 1.0
	v_mul_f32_e64 v17, v16, -v14
	v_mul_f32_e64 v12, v19, -v15
	v_fma_f32 v16, -v20, v20, 1.0
	v_cmp_lt_f32_e32 vcc, s6, v14
	v_fma_f32 v13, -v21, v21, 1.0
	s_nop 0
	v_cndmask_b32_e32 v16, v16, v17, vcc
	v_cmp_lt_f32_e32 vcc, s6, v15
	v_sqrt_f32_e32 v16, v16
	s_nop 1
	v_cndmask_b32_e32 v17, v13, v12, vcc
	v_sqrt_f32_e32 v17, v17
	s_nop 0
	v_pk_mul_f32 v[24:25], v[24:25], v[16:17]
	s_nop 0
	v_pk_mul_f32 v[24:25], v[28:29], v[24:25]
	v_fmamk_f32 v22, v22, 0xbfb8aa3b, v136
	v_fmamk_f32 v23, v23, 0xbfb8aa3b, v137
	v_fmamk_f32 v26, v26, 0xbfb8aa3b, v140
	v_fmamk_f32 v27, v27, 0xbfb8aa3b, v141
	v_exp_f32_e32 v22, v22
	v_exp_f32_e32 v23, v23
	v_exp_f32_e32 v26, v26
	v_exp_f32_e32 v27, v27
	v_add_f32_e32 v22, 1.0, v22
	v_add_f32_e32 v23, 1.0, v23
	v_add_f32_e32 v26, 1.0, v26
	v_add_f32_e32 v27, 1.0, v27
	v_rcp_f32_e32 v22, v22
	v_rcp_f32_e32 v23, v23
	v_rcp_f32_e32 v26, v26
	v_rcp_f32_e32 v27, v27
	v_pk_mul_f32 v[14:15], v[22:23], v[164:165]
	v_pk_mul_f32 v[12:13], v[22:23], v[168:169]
	s_nop 0
	v_exp_f32_e32 v22, v12
	v_exp_f32_e32 v23, v13
	v_fmaak_f32 v16, v14, v205, 0x3d2aaaab
	v_fmaak_f32 v19, v15, v205, 0x3d2aaaab
	v_fmaak_f32 v16, v16, v14, 0x3e2aaaab
	v_fmaak_f32 v19, v19, v15, 0x3e2aaaab
	v_fma_f32 v16, v16, v14, 0.5
	v_fma_f32 v19, v19, v15, 0.5
	v_fma_f32 v16, v16, v14, 1.0
	v_fma_f32 v19, v19, v15, 1.0
	v_mul_f32_e64 v17, v16, -v14
	v_mul_f32_e64 v12, v19, -v15
	v_fma_f32 v16, -v22, v22, 1.0
	v_cmp_lt_f32_e32 vcc, s6, v14
	v_fma_f32 v13, -v23, v23, 1.0
	s_nop 0
	v_cndmask_b32_e32 v16, v16, v17, vcc
	v_cmp_lt_f32_e32 vcc, s6, v15
	v_sqrt_f32_e32 v16, v16
	s_nop 1
	v_cndmask_b32_e32 v17, v13, v12, vcc
	v_sqrt_f32_e32 v17, v17
	s_nop 0
	v_pk_mul_f32 v[26:27], v[26:27], v[16:17]
	s_nop 0
	v_pk_mul_f32 v[26:27], v[30:31], v[26:27]
	ds_write_b128 v204, v[20:23] offset:42496
	ds_write_b128 v204, v[24:27] offset:58880
	ds_read_b128 v[12:15], v229 offset:32000
	ds_read_b128 v[16:19], v229 offset:32064
	ds_read_b128 v[28:31], v230 offset:20992
	s_waitcnt lgkmcnt(1)
	v_mfma_f32_16x16x32_bf16 v[20:23], v[232:235], v[12:15], 0
	v_mfma_f32_16x16x32_bf16 v[24:27], v[240:243], v[12:15], 0
	v_mfma_f32_16x16x32_bf16 v[20:23], v[236:239], v[16:19], v[20:23]
	v_mfma_f32_16x16x32_bf16 v[24:27], v[244:247], v[16:19], v[24:27]
	s_nop 7
	s_nop 3
	s_waitcnt lgkmcnt(0)
	v_fmamk_f32 v20, v20, 0xbfb8aa3b, v134
	v_fmamk_f32 v21, v21, 0xbfb8aa3b, v135
	v_fmamk_f32 v24, v24, 0xbfb8aa3b, v138
	v_fmamk_f32 v25, v25, 0xbfb8aa3b, v139
	v_exp_f32_e32 v20, v20
	v_exp_f32_e32 v21, v21
	v_exp_f32_e32 v24, v24
	v_exp_f32_e32 v25, v25
	v_add_f32_e32 v20, 1.0, v20
	v_add_f32_e32 v21, 1.0, v21
	v_add_f32_e32 v24, 1.0, v24
	v_add_f32_e32 v25, 1.0, v25
	v_rcp_f32_e32 v20, v20
	v_rcp_f32_e32 v21, v21
	v_rcp_f32_e32 v24, v24
	v_rcp_f32_e32 v25, v25
	v_pk_mul_f32 v[14:15], v[20:21], v[162:163]
	v_pk_mul_f32 v[12:13], v[20:21], v[166:167]
	s_nop 0
	v_exp_f32_e32 v20, v12
	v_exp_f32_e32 v21, v13
	v_fmaak_f32 v16, v14, v205, 0x3d2aaaab
	v_fmaak_f32 v19, v15, v205, 0x3d2aaaab
	v_fmaak_f32 v16, v16, v14, 0x3e2aaaab
	v_fmaak_f32 v19, v19, v15, 0x3e2aaaab
	v_fma_f32 v16, v16, v14, 0.5
	v_fma_f32 v19, v19, v15, 0.5
	v_fma_f32 v16, v16, v14, 1.0
	v_fma_f32 v19, v19, v15, 1.0
	v_mul_f32_e64 v17, v16, -v14
	v_mul_f32_e64 v12, v19, -v15
	v_fma_f32 v16, -v20, v20, 1.0
	v_cmp_lt_f32_e32 vcc, s6, v14
	v_fma_f32 v13, -v21, v21, 1.0
	s_nop 0
	v_cndmask_b32_e32 v16, v16, v17, vcc
	v_cmp_lt_f32_e32 vcc, s6, v15
	v_sqrt_f32_e32 v16, v16
	s_nop 1
	v_cndmask_b32_e32 v17, v13, v12, vcc
	v_sqrt_f32_e32 v17, v17
	s_nop 0
	v_pk_mul_f32 v[24:25], v[24:25], v[16:17]
	s_nop 0
	v_pk_mul_f32 v[24:25], v[28:29], v[24:25]
	v_fmamk_f32 v22, v22, 0xbfb8aa3b, v136
	v_fmamk_f32 v23, v23, 0xbfb8aa3b, v137
	v_fmamk_f32 v26, v26, 0xbfb8aa3b, v140
	v_fmamk_f32 v27, v27, 0xbfb8aa3b, v141
	v_exp_f32_e32 v22, v22
	v_exp_f32_e32 v23, v23
	v_exp_f32_e32 v26, v26
	v_exp_f32_e32 v27, v27
	v_add_f32_e32 v22, 1.0, v22
	v_add_f32_e32 v23, 1.0, v23
	v_add_f32_e32 v26, 1.0, v26
	v_add_f32_e32 v27, 1.0, v27
	v_rcp_f32_e32 v22, v22
	v_rcp_f32_e32 v23, v23
	v_rcp_f32_e32 v26, v26
	v_rcp_f32_e32 v27, v27
	v_pk_mul_f32 v[14:15], v[22:23], v[164:165]
	v_pk_mul_f32 v[12:13], v[22:23], v[168:169]
	s_nop 0
	v_exp_f32_e32 v22, v12
	v_exp_f32_e32 v23, v13
	v_fmaak_f32 v16, v14, v205, 0x3d2aaaab
	v_fmaak_f32 v19, v15, v205, 0x3d2aaaab
	v_fmaak_f32 v16, v16, v14, 0x3e2aaaab
	v_fmaak_f32 v19, v19, v15, 0x3e2aaaab
	v_fma_f32 v16, v16, v14, 0.5
	v_fma_f32 v19, v19, v15, 0.5
	v_fma_f32 v16, v16, v14, 1.0
	v_fma_f32 v19, v19, v15, 1.0
	v_mul_f32_e64 v17, v16, -v14
	v_mul_f32_e64 v12, v19, -v15
	v_fma_f32 v16, -v22, v22, 1.0
	v_cmp_lt_f32_e32 vcc, s6, v14
	v_fma_f32 v13, -v23, v23, 1.0
	s_nop 0
	v_cndmask_b32_e32 v16, v16, v17, vcc
	v_cmp_lt_f32_e32 vcc, s6, v15
	v_sqrt_f32_e32 v16, v16
	s_nop 1
	v_cndmask_b32_e32 v17, v13, v12, vcc
	v_sqrt_f32_e32 v17, v17
	s_nop 0
	v_pk_mul_f32 v[26:27], v[26:27], v[16:17]
	s_nop 0
	v_pk_mul_f32 v[26:27], v[30:31], v[26:27]
	ds_write_b128 v204, v[20:23] offset:46592
	ds_write_b128 v204, v[24:27] offset:62976
	s_waitcnt lgkmcnt(0)
	s_barrier
; template <bool FINAL>
; __device__ void phase_lru(const Params& p, int l, unsigned char* smem) {
;     ...
;       {
;         float A = 1.f, B = 0.f;
;         if (d == 0) {
; #pragma unroll
;           for (int tt = 0; tt < 16; ++tt) { int t = qd * 16 + tt; float a = sa[t * 64 + e_], b = sb[t * 64 + e_]; B = a * B + b; A *= a; }
;         } else {
; #pragma unroll
;     ...
;         }
;         part[(0 * 4 + qd) * 64 + e_] = A;
;         part[(1 * 4 + qd) * 64 + e_] = B;
;       }
;       __syncthreads();
;       if (!FINAL) {
;         if (qd == 0) {
;           float A = 1.f, B = 0.f;
;           if (d == 0) {
; #pragma unroll
;             for (int q = 0; q < 4; ++q) { float aq = part[q * 64 + e_], bq = part[(4 + q) * 64 + e_]; B = aq * B + bq; A *= aq; }
;           } else {
; #pragma unroll
;             for (int q = 3; q >= 0; --q) { float aq = part[q * 64 + e_], bq = part[(4 + q) * 64 + e_]; B = aq * B + bq; A *= aq; }
;           }
;           const size_t cidx = ((size_t)ci * 2 + d) * 512 + nb * 64 + e_;
;           p.CA[cidx] = A; p.CB[cidx] = B;
;         }
	ds_read2st64_b32 v[12:13], v96 offset0:134 offset1:198
	ds_read2st64_b32 v[14:15], v95 offset0:134 offset1:198
	ds_read2st64_b32 v[16:17], v94 offset0:134 offset1:198
	ds_read2st64_b32 v[104:105], v83 offset0:134 offset1:198
	ds_read2st64_b32 v[106:107], v82 offset0:134 offset1:198
	s_waitcnt lgkmcnt(4)
	v_fmac_f32_e32 v13, 0, v12
	s_waitcnt lgkmcnt(3)
	v_mul_f32_e32 v18, v12, v14
	s_waitcnt lgkmcnt(2)
	v_mul_f32_e32 v20, v18, v16
	ds_read2st64_b32 v[18:19], v93 offset0:134 offset1:198
	v_fmac_f32_e32 v15, v14, v13
	v_fmac_f32_e32 v17, v16, v15
	ds_read2st64_b32 v[108:109], v49 offset0:134 offset1:198
	s_waitcnt lgkmcnt(1)
	v_mul_f32_e32 v22, v20, v18
	ds_read2st64_b32 v[20:21], v92 offset0:134 offset1:198
	v_fmac_f32_e32 v19, v18, v17
	s_waitcnt lgkmcnt(0)
	v_mul_f32_e32 v24, v22, v20
	ds_read2st64_b32 v[22:23], v91 offset0:134 offset1:198
	v_fmac_f32_e32 v21, v20, v19
	s_waitcnt lgkmcnt(0)
	v_mul_f32_e32 v26, v24, v22
	ds_read2st64_b32 v[24:25], v90 offset0:134 offset1:198
	v_fmac_f32_e32 v23, v22, v21
	s_waitcnt lgkmcnt(0)
	v_mul_f32_e32 v28, v26, v24
	ds_read2st64_b32 v[26:27], v89 offset0:134 offset1:198
	v_fmac_f32_e32 v25, v24, v23
	s_waitcnt lgkmcnt(0)
	v_mul_f32_e32 v30, v28, v26
	ds_read2st64_b32 v[28:29], v88 offset0:134 offset1:198
	v_fmac_f32_e32 v27, v26, v25
	s_waitcnt lgkmcnt(0)
	v_mul_f32_e32 v32, v30, v28
	ds_read2st64_b32 v[30:31], v87 offset0:134 offset1:198
	v_fmac_f32_e32 v29, v28, v27
	s_waitcnt lgkmcnt(0)
	v_mul_f32_e32 v34, v32, v30
	ds_read2st64_b32 v[32:33], v86 offset0:134 offset1:198
	v_fmac_f32_e32 v31, v30, v29
	s_waitcnt lgkmcnt(0)
	v_mul_f32_e32 v54, v34, v32
	ds_read2st64_b32 v[34:35], v85 offset0:134 offset1:198
	v_fmac_f32_e32 v33, v32, v31
	s_waitcnt lgkmcnt(0)
	v_mul_f32_e32 v56, v54, v34
	ds_read2st64_b32 v[54:55], v84 offset0:134 offset1:198
	v_fmac_f32_e32 v35, v34, v33
	s_waitcnt lgkmcnt(0)
	v_mul_f32_e32 v56, v56, v54
	v_mul_f32_e32 v56, v56, v104
	v_fmac_f32_e32 v55, v54, v35
	v_mul_f32_e32 v56, v56, v106
	v_fmac_f32_e32 v105, v104, v55
	v_mul_f32_e32 v56, v56, v108
	v_fmac_f32_e32 v107, v106, v105
	v_fmac_f32_e32 v109, v108, v107
	ds_write_b32 v64, v56
	ds_write_b32 v65, v109 offset:1024
	s_waitcnt lgkmcnt(0)
	s_barrier
	s_and_saveexec_b64 s[42:43], s[40:41]
	s_cbranch_execz .LBB0_374
	ds_read2st64_b32 v[12:13], v64 offset0:2 offset1:3
	ds_read2st64_b32 v[14:15], v64 offset1:1
	ds_read_b32 v17, v97
	s_waitcnt lgkmcnt(2)
	v_mul_f32_e32 v16, v13, v12
	s_waitcnt lgkmcnt(1)
	v_mul_f32_e32 v16, v16, v15
	s_waitcnt lgkmcnt(0)
	v_fmac_f32_e32 v17, 0, v13
	ds_read_b32 v13, v98
	v_mul_f32_e32 v16, v16, v14
	s_waitcnt lgkmcnt(0)
	v_fmac_f32_e32 v13, v12, v17
	ds_read_b32 v12, v99
	s_waitcnt lgkmcnt(0)
	v_fmac_f32_e32 v12, v15, v13
	ds_read_b32 v13, v100
	s_waitcnt lgkmcnt(0)
	v_fmac_f32_e32 v13, v14, v12
	global_store_dword v[50:51], v16, off offset:2048
	global_store_dword v[52:53], v13, off offset:2048
	s_branch .LBB0_374
